# removed the back-to-back s_setprio 0/1 pair inside every 32-MFMA segment of the six GEMM loops (on top of the union version)
# baseline (speedup 1.0000x reference)
; #define PG8_STAGE(bufoff, gbase, voff) do { _Pragma("unroll") for (int _i = 0; _i < 2; ++_i) \
;         __builtin_amdgcn_global_load_lds((const unsigned*)((const char*)(gbase) + (voff)[_i]), (PG8_LAS unsigned*)(lds + (bufoff) + ldsw + _i * 8192), 16, 0, 0); } while (0)
; #define PG8_LDA(dst, b, h) do { _Pragma("unroll") for (int m = 0; m < 4; ++m) _Pragma("unroll") for (int k = 0; k < 2; ++k) dst[m][k] = *(const PG8_LAS bf16x8*)(lds + PG8_SA(b, h) + aoff + m * 2048 + k * 1024); } while (0)
; #define PG8_LDB(dst, b, h) do { _Pragma("unroll") for (int n = 0; n < 2; ++n) _Pragma("unroll") for (int k = 0; k < 2; ++k) dst[n][k] = *(const PG8_LAS bf16x8*)(lds + PG8_SB(b, h) + boff + n * 2048 + k * 1024); } while (0)
; #define PG8_MMA(ai, bj, At, Bt) do { __builtin_amdgcn_s_setprio(1); _Pragma("unroll") for (int m = 0; m < 4; ++m) _Pragma("unroll") for (int n = 0; n < 2; ++n) _Pragma("unroll") for (int k = 0; k < 2; ++k) \
;         acc[ai][bj][m][n] = __builtin_amdgcn_mfma_f32_16x16x32_bf16(Bt[n][k], At[m][k], acc[ai][bj][m][n], 0, 0, 0); __builtin_amdgcn_s_setprio(0); } while (0)
; #define PG8_WAIT_V(n) asm volatile("s_waitcnt vmcnt(" #n ")" ::: "memory")
; #define PG8_WAIT_L(n) asm volatile("s_waitcnt lgkmcnt(" #n ")" ::: "memory")
; #define PG8_BAR __builtin_amdgcn_s_barrier()
; #define PG8_SCHED __builtin_amdgcn_sched_barrier(0)
; template <class Epi, class Sched>
; __device__ __forceinline__ void gemm_phase(PG8_LAS unsigned char* lds, const Gemm g, const Sched& S, const Epi& E) {
;     ...
;             PG8_LDB(B0, 0, 0); PG8_LDB(B1, 0, 1); PG8_SCHED; PG8_LDA(At, 0, 0); PG8_STAGE(PG8_SA(1, 1), a1 + hstepA, voffA);
;             PG8_WAIT_V(8); PG8_WAIT_L(0); PG8_BAR; PG8_MMA(0, 0, At, B0); PG8_MMA(0, 1, At, B1); PG8_BAR; PG8_SCHED;
;             PG8_LDA(At, 0, 1); PG8_STAGE(PG8_SB(0, 0), b2, voffB); PG8_STAGE(PG8_SB(0, 1), b2 + hstepB, voffB); PG8_STAGE(PG8_SA(0, 0), a2, voffA);
;             PG8_WAIT_V(8); PG8_WAIT_L(0); PG8_BAR; PG8_MMA(1, 0, At, B0); PG8_MMA(1, 1, At, B1); PG8_BAR; PG8_SCHED;
.LBB0_120:
	ds_read_b128 v[150:153], v146
	ds_read_b128 v[156:159], v146 offset:1024
	ds_read_b128 v[160:163], v146 offset:2048
	ds_read_b128 v[164:167], v146 offset:3072
	ds_read_b128 v[168:171], v147
	ds_read_b128 v[172:175], v147 offset:1024
	ds_read_b128 v[176:179], v147 offset:2048
	ds_read_b128 v[180:183], v147 offset:3072
	s_add_u32 s26, s24, 0xfff80080
	s_addc_u32 s27, s25, -1
	s_cmp_eq_u32 s51, 4
	s_cselect_b32 s29, s21, s27
	s_cselect_b32 s28, s20, s26
	s_cselect_b32 s27, s15, s50
	s_cselect_b32 s26, s17, s49
	v_lshl_add_u64 v[216:217], s[24:25], 0, v[140:141]
	s_add_i32 m0, s37, 0xc000
	ds_read_b128 v[184:187], v148
	ds_read_b128 v[188:191], v148 offset:1024
	ds_read_b128 v[192:195], v148 offset:2048
	ds_read_b128 v[196:199], v148 offset:3072
	ds_read_b128 v[200:203], v148 offset:4096
	ds_read_b128 v[204:207], v148 offset:5120
	ds_read_b128 v[208:211], v148 offset:6144
	ds_read_b128 v[212:215], v148 offset:7168
	global_load_lds_dwordx4 v[216:217], off
	v_lshl_add_u64 v[216:217], s[24:25], 0, v[142:143]
	s_add_i32 m0, s37, 0xe000
	s_nop 0
	global_load_lds_dwordx4 v[216:217], off
	s_waitcnt vmcnt(8)
	s_waitcnt lgkmcnt(0)
	s_barrier
	s_setprio 1
	s_waitcnt lgkmcnt(0)
	v_mfma_f32_16x16x32_bf16 v[126:129], v[150:153], v[184:187], v[126:129]
	v_mfma_f32_16x16x32_bf16 v[122:125], v[160:163], v[184:187], v[122:125]
	v_mfma_f32_16x16x32_bf16 v[118:121], v[150:153], v[192:195], v[118:121]
	v_mfma_f32_16x16x32_bf16 v[110:113], v[160:163], v[192:195], v[110:113]
	v_mfma_f32_16x16x32_bf16 v[102:105], v[150:153], v[200:203], v[102:105]
	v_mfma_f32_16x16x32_bf16 v[94:97], v[160:163], v[200:203], v[94:97]
	v_mfma_f32_16x16x32_bf16 v[86:89], v[150:153], v[208:211], v[86:89]
	v_mfma_f32_16x16x32_bf16 v[78:81], v[160:163], v[208:211], v[78:81]
	v_mfma_f32_16x16x32_bf16 v[126:129], v[156:159], v[188:191], v[126:129]
	v_mfma_f32_16x16x32_bf16 v[122:125], v[164:167], v[188:191], v[122:125]
	v_mfma_f32_16x16x32_bf16 v[118:121], v[156:159], v[196:199], v[118:121]
	v_mfma_f32_16x16x32_bf16 v[110:113], v[164:167], v[196:199], v[110:113]
	v_mfma_f32_16x16x32_bf16 v[102:105], v[156:159], v[204:207], v[102:105]
	v_mfma_f32_16x16x32_bf16 v[94:97], v[164:167], v[204:207], v[94:97]
	v_mfma_f32_16x16x32_bf16 v[86:89], v[156:159], v[212:215], v[86:89]
	v_mfma_f32_16x16x32_bf16 v[78:81], v[164:167], v[212:215], v[78:81]
	v_mfma_f32_16x16x32_bf16 v[114:117], v[168:171], v[184:187], v[114:117]
	v_mfma_f32_16x16x32_bf16 v[106:109], v[176:179], v[184:187], v[106:109]
	v_mfma_f32_16x16x32_bf16 v[98:101], v[168:171], v[192:195], v[98:101]
	v_mfma_f32_16x16x32_bf16 v[90:93], v[176:179], v[192:195], v[90:93]
	v_mfma_f32_16x16x32_bf16 v[82:85], v[168:171], v[200:203], v[82:85]
	v_mfma_f32_16x16x32_bf16 v[74:77], v[176:179], v[200:203], v[74:77]
	v_mfma_f32_16x16x32_bf16 v[70:73], v[168:171], v[208:211], v[70:73]
	v_mfma_f32_16x16x32_bf16 v[66:69], v[176:179], v[208:211], v[66:69]
	v_mfma_f32_16x16x32_bf16 v[114:117], v[172:175], v[188:191], v[114:117]
	v_mfma_f32_16x16x32_bf16 v[106:109], v[180:183], v[188:191], v[106:109]
	v_mfma_f32_16x16x32_bf16 v[98:101], v[172:175], v[196:199], v[98:101]
	v_mfma_f32_16x16x32_bf16 v[90:93], v[180:183], v[196:199], v[90:93]
	v_mfma_f32_16x16x32_bf16 v[82:85], v[172:175], v[204:207], v[82:85]
	v_mfma_f32_16x16x32_bf16 v[74:77], v[180:183], v[204:207], v[74:77]
	v_mfma_f32_16x16x32_bf16 v[70:73], v[172:175], v[212:215], v[70:73]
	v_mfma_f32_16x16x32_bf16 v[66:69], v[180:183], v[212:215], v[66:69]
	s_setprio 0
	s_barrier
	s_add_i32 s52, s45, s36
	v_lshl_add_u64 v[216:217], s[26:27], 0, v[132:133]
	s_mov_b32 m0, s52
	ds_read_b128 v[184:187], v148 offset:16384
	ds_read_b128 v[188:191], v148 offset:17408
	ds_read_b128 v[192:195], v148 offset:18432
	ds_read_b128 v[196:199], v148 offset:19456
	ds_read_b128 v[200:203], v148 offset:20480
	ds_read_b128 v[204:207], v148 offset:21504
	ds_read_b128 v[208:211], v148 offset:22528
	ds_read_b128 v[212:215], v148 offset:23552
	global_load_lds_dwordx4 v[216:217], off
	s_add_i32 m0, s52, 0x2000
	s_add_u32 s52, s26, 0x20000
	v_lshl_add_u64 v[218:219], s[26:27], 0, v[136:137]
	s_addc_u32 s53, s27, 0
	s_add_i32 s54, s46, s36
	global_load_lds_dwordx4 v[218:219], off
	v_lshl_add_u64 v[220:221], s[52:53], 0, v[132:133]
	s_mov_b32 m0, s54
	v_lshl_add_u64 v[222:223], s[28:29], 0, v[134:135]
	global_load_lds_dwordx4 v[220:221], off
	v_lshl_add_u64 v[220:221], s[52:53], 0, v[136:137]
	s_add_i32 m0, s54, 0x2000
	s_nop 0
	global_load_lds_dwordx4 v[220:221], off
	v_lshl_add_u64 v[220:221], s[28:29], 0, v[130:131]
	s_mov_b32 m0, s37
	s_nop 0
	global_load_lds_dwordx4 v[220:221], off
	s_mov_b32 m0, s38
	s_nop 0
	global_load_lds_dwordx4 v[222:223], off
	s_waitcnt vmcnt(8)
	s_waitcnt lgkmcnt(0)
	s_barrier
; #define PG8_STAGE(bufoff, gbase, voff) do { _Pragma("unroll") for (int _i = 0; _i < 2; ++_i) \
;         __builtin_amdgcn_global_load_lds((const unsigned*)((const char*)(gbase) + (voff)[_i]), (PG8_LAS unsigned*)(lds + (bufoff) + ldsw + _i * 8192), 16, 0, 0); } while (0)
; #define PG8_LDA(dst, b, h) do { _Pragma("unroll") for (int m = 0; m < 4; ++m) _Pragma("unroll") for (int k = 0; k < 2; ++k) dst[m][k] = *(const PG8_LAS bf16x8*)(lds + PG8_SA(b, h) + aoff + m * 2048 + k * 1024); } while (0)
; #define PG8_LDB(dst, b, h) do { _Pragma("unroll") for (int n = 0; n < 2; ++n) _Pragma("unroll") for (int k = 0; k < 2; ++k) dst[n][k] = *(const PG8_LAS bf16x8*)(lds + PG8_SB(b, h) + boff + n * 2048 + k * 1024); } while (0)
; #define PG8_MMA(ai, bj, At, Bt) do { __builtin_amdgcn_s_setprio(1); _Pragma("unroll") for (int m = 0; m < 4; ++m) _Pragma("unroll") for (int n = 0; n < 2; ++n) _Pragma("unroll") for (int k = 0; k < 2; ++k) \
;         acc[ai][bj][m][n] = __builtin_amdgcn_mfma_f32_16x16x32_bf16(Bt[n][k], At[m][k], acc[ai][bj][m][n], 0, 0, 0); __builtin_amdgcn_s_setprio(0); } while (0)
; #define PG8_WAIT_V(n) asm volatile("s_waitcnt vmcnt(" #n ")" ::: "memory")
; #define PG8_WAIT_L(n) asm volatile("s_waitcnt lgkmcnt(" #n ")" ::: "memory")
; #define PG8_BAR __builtin_amdgcn_s_barrier()
; #define PG8_SCHED __builtin_amdgcn_sched_barrier(0)
; template <class Epi, class Sched>
; __device__ __forceinline__ void gemm_phase(PG8_LAS unsigned char* lds, const Gemm g, const Sched& S, const Epi& E) {
;     ...
;             PG8_WAIT_V(8); PG8_WAIT_L(0); PG8_BAR; PG8_MMA(1, 0, At, B0); PG8_MMA(1, 1, At, B1); PG8_BAR; PG8_SCHED;
;             PG8_LDB(B0, 1, 0); PG8_LDB(B1, 1, 1); PG8_SCHED; PG8_LDA(At, 1, 0); PG8_STAGE(PG8_SA(0, 1), a2 + hstepA, voffA);
;             PG8_WAIT_V(8); PG8_WAIT_L(0); PG8_BAR; PG8_MMA(0, 0, At, B0); PG8_MMA(0, 1, At, B1); PG8_BAR; PG8_SCHED;
;             PG8_LDA(At, 1, 1); PG8_STAGE(PG8_SB(1, 0), b3, voffB); PG8_STAGE(PG8_SB(1, 1), b3 + hstepB, voffB); PG8_STAGE(PG8_SA(1, 0), a3, voffA);
	s_setprio 1
	s_waitcnt lgkmcnt(0)
	v_mfma_f32_16x16x32_bf16 v[62:65], v[150:153], v[184:187], v[62:65]
	v_mfma_f32_16x16x32_bf16 v[58:61], v[160:163], v[184:187], v[58:61]
	v_mfma_f32_16x16x32_bf16 v[54:57], v[150:153], v[192:195], v[54:57]
	v_mfma_f32_16x16x32_bf16 v[46:49], v[160:163], v[192:195], v[46:49]
	v_mfma_f32_16x16x32_bf16 v[38:41], v[150:153], v[200:203], v[38:41]
	v_mfma_f32_16x16x32_bf16 v[30:33], v[160:163], v[200:203], v[30:33]
	v_mfma_f32_16x16x32_bf16 v[22:25], v[150:153], v[208:211], v[22:25]
	v_mfma_f32_16x16x32_bf16 v[14:17], v[160:163], v[208:211], v[14:17]
	v_mfma_f32_16x16x32_bf16 v[62:65], v[156:159], v[188:191], v[62:65]
	v_mfma_f32_16x16x32_bf16 v[58:61], v[164:167], v[188:191], v[58:61]
	v_mfma_f32_16x16x32_bf16 v[54:57], v[156:159], v[196:199], v[54:57]
	v_mfma_f32_16x16x32_bf16 v[46:49], v[164:167], v[196:199], v[46:49]
	v_mfma_f32_16x16x32_bf16 v[38:41], v[156:159], v[204:207], v[38:41]
	v_mfma_f32_16x16x32_bf16 v[30:33], v[164:167], v[204:207], v[30:33]
	v_mfma_f32_16x16x32_bf16 v[22:25], v[156:159], v[212:215], v[22:25]
	v_mfma_f32_16x16x32_bf16 v[14:17], v[164:167], v[212:215], v[14:17]
	v_mfma_f32_16x16x32_bf16 v[50:53], v[168:171], v[184:187], v[50:53]
	v_mfma_f32_16x16x32_bf16 v[42:45], v[176:179], v[184:187], v[42:45]
	v_mfma_f32_16x16x32_bf16 v[34:37], v[168:171], v[192:195], v[34:37]
	v_mfma_f32_16x16x32_bf16 v[26:29], v[176:179], v[192:195], v[26:29]
	v_mfma_f32_16x16x32_bf16 v[18:21], v[168:171], v[200:203], v[18:21]
	v_mfma_f32_16x16x32_bf16 v[10:13], v[176:179], v[200:203], v[10:13]
	v_mfma_f32_16x16x32_bf16 v[6:9], v[168:171], v[208:211], v[6:9]
	v_mfma_f32_16x16x32_bf16 v[2:5], v[176:179], v[208:211], v[2:5]
	v_mfma_f32_16x16x32_bf16 v[50:53], v[172:175], v[188:191], v[50:53]
	v_mfma_f32_16x16x32_bf16 v[42:45], v[180:183], v[188:191], v[42:45]
	v_mfma_f32_16x16x32_bf16 v[34:37], v[172:175], v[196:199], v[34:37]
	v_mfma_f32_16x16x32_bf16 v[26:29], v[180:183], v[196:199], v[26:29]
	v_mfma_f32_16x16x32_bf16 v[18:21], v[172:175], v[204:207], v[18:21]
	v_mfma_f32_16x16x32_bf16 v[10:13], v[180:183], v[204:207], v[10:13]
	v_mfma_f32_16x16x32_bf16 v[6:9], v[172:175], v[212:215], v[6:9]
	v_mfma_f32_16x16x32_bf16 v[2:5], v[180:183], v[212:215], v[2:5]
	s_setprio 0
	s_barrier
	s_add_i32 s52, 0, 0x18000
	v_add_u32_e32 v149, s52, v145
	s_add_i32 s53, 0, 0x1c000
	ds_read_b128 v[150:153], v149
	ds_read_b128 v[156:159], v149 offset:1024
	ds_read_b128 v[160:163], v149 offset:2048
	ds_read_b128 v[164:167], v149 offset:3072
	v_add_u32_e32 v149, s53, v145
	ds_read_b128 v[168:171], v149
	ds_read_b128 v[172:175], v149 offset:1024
	ds_read_b128 v[176:179], v149 offset:2048
	ds_read_b128 v[180:183], v149 offset:3072
	s_add_u32 s28, s28, 0x80000
	s_addc_u32 s29, s29, 0
	s_mov_b32 m0, s39
	v_lshl_add_u64 v[224:225], s[28:29], 0, v[130:131]
	ds_read_b128 v[184:187], v148 offset:32768
	ds_read_b128 v[188:191], v148 offset:33792
	ds_read_b128 v[192:195], v148 offset:34816
	ds_read_b128 v[196:199], v148 offset:35840
	ds_read_b128 v[200:203], v148 offset:36864
	ds_read_b128 v[204:207], v148 offset:37888
	ds_read_b128 v[208:211], v148 offset:38912
	ds_read_b128 v[212:215], v148 offset:39936
	global_load_lds_dwordx4 v[224:225], off
	v_lshl_add_u64 v[224:225], s[28:29], 0, v[134:135]
	s_mov_b32 m0, s40
	s_nop 0
	global_load_lds_dwordx4 v[224:225], off
	s_waitcnt vmcnt(8)
	s_waitcnt lgkmcnt(0)
	s_barrier
	s_setprio 1
	s_waitcnt lgkmcnt(0)
	v_mfma_f32_16x16x32_bf16 v[126:129], v[150:153], v[184:187], v[126:129]
	v_mfma_f32_16x16x32_bf16 v[122:125], v[160:163], v[184:187], v[122:125]
	v_mfma_f32_16x16x32_bf16 v[118:121], v[150:153], v[192:195], v[118:121]
	v_mfma_f32_16x16x32_bf16 v[110:113], v[160:163], v[192:195], v[110:113]
	v_mfma_f32_16x16x32_bf16 v[102:105], v[150:153], v[200:203], v[102:105]
	v_mfma_f32_16x16x32_bf16 v[94:97], v[160:163], v[200:203], v[94:97]
	v_mfma_f32_16x16x32_bf16 v[86:89], v[150:153], v[208:211], v[86:89]
	v_mfma_f32_16x16x32_bf16 v[78:81], v[160:163], v[208:211], v[78:81]
	v_mfma_f32_16x16x32_bf16 v[126:129], v[156:159], v[188:191], v[126:129]
	v_mfma_f32_16x16x32_bf16 v[122:125], v[164:167], v[188:191], v[122:125]
	v_mfma_f32_16x16x32_bf16 v[118:121], v[156:159], v[196:199], v[118:121]
	v_mfma_f32_16x16x32_bf16 v[110:113], v[164:167], v[196:199], v[110:113]
	v_mfma_f32_16x16x32_bf16 v[102:105], v[156:159], v[204:207], v[102:105]
	v_mfma_f32_16x16x32_bf16 v[94:97], v[164:167], v[204:207], v[94:97]
	v_mfma_f32_16x16x32_bf16 v[86:89], v[156:159], v[212:215], v[86:89]
	v_mfma_f32_16x16x32_bf16 v[78:81], v[164:167], v[212:215], v[78:81]
	v_mfma_f32_16x16x32_bf16 v[114:117], v[168:171], v[184:187], v[114:117]
	v_mfma_f32_16x16x32_bf16 v[106:109], v[176:179], v[184:187], v[106:109]
	v_mfma_f32_16x16x32_bf16 v[98:101], v[168:171], v[192:195], v[98:101]
	v_mfma_f32_16x16x32_bf16 v[90:93], v[176:179], v[192:195], v[90:93]
	v_mfma_f32_16x16x32_bf16 v[82:85], v[168:171], v[200:203], v[82:85]
	v_mfma_f32_16x16x32_bf16 v[74:77], v[176:179], v[200:203], v[74:77]
	v_mfma_f32_16x16x32_bf16 v[70:73], v[168:171], v[208:211], v[70:73]
	v_mfma_f32_16x16x32_bf16 v[66:69], v[176:179], v[208:211], v[66:69]
	v_mfma_f32_16x16x32_bf16 v[114:117], v[172:175], v[188:191], v[114:117]
	v_mfma_f32_16x16x32_bf16 v[106:109], v[180:183], v[188:191], v[106:109]
	v_mfma_f32_16x16x32_bf16 v[98:101], v[172:175], v[196:199], v[98:101]
	v_mfma_f32_16x16x32_bf16 v[90:93], v[180:183], v[196:199], v[90:93]
	v_mfma_f32_16x16x32_bf16 v[82:85], v[172:175], v[204:207], v[82:85]
	v_mfma_f32_16x16x32_bf16 v[74:77], v[180:183], v[204:207], v[74:77]
	v_mfma_f32_16x16x32_bf16 v[70:73], v[172:175], v[212:215], v[70:73]
	v_mfma_f32_16x16x32_bf16 v[66:69], v[180:183], v[212:215], v[66:69]
	s_setprio 0
	s_barrier
; #define PG8_STAGE(bufoff, gbase, voff) do { _Pragma("unroll") for (int _i = 0; _i < 2; ++_i) \
;         __builtin_amdgcn_global_load_lds((const unsigned*)((const char*)(gbase) + (voff)[_i]), (PG8_LAS unsigned*)(lds + (bufoff) + ldsw + _i * 8192), 16, 0, 0); } while (0)
; #define PG8_LDA(dst, b, h) do { _Pragma("unroll") for (int m = 0; m < 4; ++m) _Pragma("unroll") for (int k = 0; k < 2; ++k) dst[m][k] = *(const PG8_LAS bf16x8*)(lds + PG8_SA(b, h) + aoff + m * 2048 + k * 1024); } while (0)
; #define PG8_MMA(ai, bj, At, Bt) do { __builtin_amdgcn_s_setprio(1); _Pragma("unroll") for (int m = 0; m < 4; ++m) _Pragma("unroll") for (int n = 0; n < 2; ++n) _Pragma("unroll") for (int k = 0; k < 2; ++k) \
;         acc[ai][bj][m][n] = __builtin_amdgcn_mfma_f32_16x16x32_bf16(Bt[n][k], At[m][k], acc[ai][bj][m][n], 0, 0, 0); __builtin_amdgcn_s_setprio(0); } while (0)
; #define PG8_WAIT_V(n) asm volatile("s_waitcnt vmcnt(" #n ")" ::: "memory")
; #define PG8_WAIT_L(n) asm volatile("s_waitcnt lgkmcnt(" #n ")" ::: "memory")
; #define PG8_BAR __builtin_amdgcn_s_barrier()
; #define PG8_SCHED __builtin_amdgcn_sched_barrier(0)
; template <class Epi, class Sched>
; __device__ __forceinline__ void gemm_phase(PG8_LAS unsigned char* lds, const Gemm g, const Sched& S, const Epi& E) {
;     ...
;             PG8_LDA(At, 1, 1); PG8_STAGE(PG8_SB(1, 0), b3, voffB); PG8_STAGE(PG8_SB(1, 1), b3 + hstepB, voffB); PG8_STAGE(PG8_SA(1, 0), a3, voffA);
;             PG8_WAIT_V(8); PG8_WAIT_L(0); PG8_BAR; PG8_MMA(1, 0, At, B0); PG8_MMA(1, 1, At, B1); PG8_BAR; PG8_SCHED;
;         }
	s_add_i32 s28, s52, s36
	v_lshl_add_u64 v[216:217], v[216:217], 0, s[8:9]
	s_mov_b32 m0, s28
	ds_read_b128 v[184:187], v148 offset:49152
	ds_read_b128 v[188:191], v148 offset:50176
	ds_read_b128 v[192:195], v148 offset:51200
	ds_read_b128 v[196:199], v148 offset:52224
	ds_read_b128 v[200:203], v148 offset:53248
	ds_read_b128 v[204:207], v148 offset:54272
	ds_read_b128 v[208:211], v148 offset:55296
	ds_read_b128 v[212:215], v148 offset:56320
	global_load_lds_dwordx4 v[216:217], off
	s_add_i32 m0, s28, 0x2000
	s_add_u32 s26, s26, 0x20080
	v_lshl_add_u64 v[216:217], v[218:219], 0, s[8:9]
	s_addc_u32 s27, s27, 0
	s_add_i32 s28, s53, s36
	global_load_lds_dwordx4 v[216:217], off
	v_lshl_add_u64 v[216:217], s[26:27], 0, v[132:133]
	s_mov_b32 m0, s28
	s_nop 0
	global_load_lds_dwordx4 v[216:217], off
	v_lshl_add_u64 v[216:217], s[26:27], 0, v[136:137]
	s_add_i32 m0, s28, 0x2000
	s_nop 0
	global_load_lds_dwordx4 v[216:217], off
	v_lshl_add_u64 v[216:217], v[220:221], 0, s[8:9]
	s_mov_b32 m0, s42
	s_nop 0
	global_load_lds_dwordx4 v[216:217], off
	v_lshl_add_u64 v[216:217], v[222:223], 0, s[8:9]
	s_mov_b32 m0, s43
	s_nop 0
	global_load_lds_dwordx4 v[216:217], off
	s_waitcnt vmcnt(8)
	s_waitcnt lgkmcnt(0)
	s_barrier
	s_setprio 1
	s_waitcnt lgkmcnt(0)
	v_mfma_f32_16x16x32_bf16 v[62:65], v[150:153], v[184:187], v[62:65]
	v_mfma_f32_16x16x32_bf16 v[58:61], v[160:163], v[184:187], v[58:61]
	v_mfma_f32_16x16x32_bf16 v[54:57], v[150:153], v[192:195], v[54:57]
	v_mfma_f32_16x16x32_bf16 v[46:49], v[160:163], v[192:195], v[46:49]
	v_mfma_f32_16x16x32_bf16 v[38:41], v[150:153], v[200:203], v[38:41]
	v_mfma_f32_16x16x32_bf16 v[30:33], v[160:163], v[200:203], v[30:33]
	v_mfma_f32_16x16x32_bf16 v[22:25], v[150:153], v[208:211], v[22:25]
	v_mfma_f32_16x16x32_bf16 v[14:17], v[160:163], v[208:211], v[14:17]
	v_mfma_f32_16x16x32_bf16 v[62:65], v[156:159], v[188:191], v[62:65]
	v_mfma_f32_16x16x32_bf16 v[58:61], v[164:167], v[188:191], v[58:61]
	v_mfma_f32_16x16x32_bf16 v[54:57], v[156:159], v[196:199], v[54:57]
	v_mfma_f32_16x16x32_bf16 v[46:49], v[164:167], v[196:199], v[46:49]
	v_mfma_f32_16x16x32_bf16 v[38:41], v[156:159], v[204:207], v[38:41]
	v_mfma_f32_16x16x32_bf16 v[30:33], v[164:167], v[204:207], v[30:33]
	v_mfma_f32_16x16x32_bf16 v[22:25], v[156:159], v[212:215], v[22:25]
	v_mfma_f32_16x16x32_bf16 v[14:17], v[164:167], v[212:215], v[14:17]
	v_mfma_f32_16x16x32_bf16 v[50:53], v[168:171], v[184:187], v[50:53]
	v_mfma_f32_16x16x32_bf16 v[42:45], v[176:179], v[184:187], v[42:45]
	v_mfma_f32_16x16x32_bf16 v[34:37], v[168:171], v[192:195], v[34:37]
	v_mfma_f32_16x16x32_bf16 v[26:29], v[176:179], v[192:195], v[26:29]
	v_mfma_f32_16x16x32_bf16 v[18:21], v[168:171], v[200:203], v[18:21]
	v_mfma_f32_16x16x32_bf16 v[10:13], v[176:179], v[200:203], v[10:13]
	v_mfma_f32_16x16x32_bf16 v[6:9], v[168:171], v[208:211], v[6:9]
	v_mfma_f32_16x16x32_bf16 v[2:5], v[176:179], v[208:211], v[2:5]
	v_mfma_f32_16x16x32_bf16 v[50:53], v[172:175], v[188:191], v[50:53]
	v_mfma_f32_16x16x32_bf16 v[42:45], v[180:183], v[188:191], v[42:45]
	v_mfma_f32_16x16x32_bf16 v[34:37], v[172:175], v[196:199], v[34:37]
	v_mfma_f32_16x16x32_bf16 v[26:29], v[180:183], v[196:199], v[26:29]
	v_mfma_f32_16x16x32_bf16 v[18:21], v[172:175], v[204:207], v[18:21]
	v_mfma_f32_16x16x32_bf16 v[10:13], v[180:183], v[204:207], v[10:13]
	v_mfma_f32_16x16x32_bf16 v[6:9], v[172:175], v[212:215], v[6:9]
	v_mfma_f32_16x16x32_bf16 v[2:5], v[180:183], v[212:215], v[2:5]
	s_setprio 0
	s_barrier
	s_add_i32 s51, s51, 2
	s_add_u32 s24, s24, 0x100
	s_addc_u32 s25, s25, 0
	s_add_u32 s49, s49, 0x100
	s_addc_u32 s50, s50, 0
	s_cmp_gt_u32 s51, 5
	s_cbranch_scc0 .LBB0_120
	s_and_b64 vcc, exec, s[10:11]
	s_cbranch_vccz .LBB0_123
	s_barrier

; #define PG8_STAGE(bufoff, gbase, voff) do { _Pragma("unroll") for (int _i = 0; _i < 2; ++_i) \
;         __builtin_amdgcn_global_load_lds((const unsigned*)((const char*)(gbase) + (voff)[_i]), (PG8_LAS unsigned*)(lds + (bufoff) + ldsw + _i * 8192), 16, 0, 0); } while (0)
; #define PG8_LDA(dst, b, h) do { _Pragma("unroll") for (int m = 0; m < 4; ++m) _Pragma("unroll") for (int k = 0; k < 2; ++k) dst[m][k] = *(const PG8_LAS bf16x8*)(lds + PG8_SA(b, h) + aoff + m * 2048 + k * 1024); } while (0)
; #define PG8_LDB(dst, b, h) do { _Pragma("unroll") for (int n = 0; n < 2; ++n) _Pragma("unroll") for (int k = 0; k < 2; ++k) dst[n][k] = *(const PG8_LAS bf16x8*)(lds + PG8_SB(b, h) + boff + n * 2048 + k * 1024); } while (0)
; #define PG8_MMA(ai, bj, At, Bt) do { __builtin_amdgcn_s_setprio(1); _Pragma("unroll") for (int m = 0; m < 4; ++m) _Pragma("unroll") for (int n = 0; n < 2; ++n) _Pragma("unroll") for (int k = 0; k < 2; ++k) \
;         acc[ai][bj][m][n] = __builtin_amdgcn_mfma_f32_16x16x32_bf16(Bt[n][k], At[m][k], acc[ai][bj][m][n], 0, 0, 0); __builtin_amdgcn_s_setprio(0); } while (0)
; #define PG8_WAIT_V(n) asm volatile("s_waitcnt vmcnt(" #n ")" ::: "memory")
; #define PG8_WAIT_L(n) asm volatile("s_waitcnt lgkmcnt(" #n ")" ::: "memory")
; #define PG8_BAR __builtin_amdgcn_s_barrier()
; #define PG8_SCHED __builtin_amdgcn_sched_barrier(0)
; template <class Epi, class Sched>
; __device__ __forceinline__ void gemm_phase(PG8_LAS unsigned char* lds, const Gemm g, const Sched& S, const Epi& E) {
;     ...
;             PG8_LDB(B0, 0, 0); PG8_LDB(B1, 0, 1); PG8_SCHED; PG8_LDA(At, 0, 0); PG8_STAGE(PG8_SA(1, 1), a1 + hstepA, voffA);
;             PG8_WAIT_V(8); PG8_WAIT_L(0); PG8_BAR; PG8_MMA(0, 0, At, B0); PG8_MMA(0, 1, At, B1); PG8_BAR; PG8_SCHED;
;             PG8_LDA(At, 0, 1); PG8_STAGE(PG8_SB(0, 0), b2, voffB); PG8_STAGE(PG8_SB(0, 1), b2 + hstepB, voffB); PG8_STAGE(PG8_SA(0, 0), a2, voffA);
;             PG8_WAIT_V(8); PG8_WAIT_L(0); PG8_BAR; PG8_MMA(1, 0, At, B0); PG8_MMA(1, 1, At, B1); PG8_BAR; PG8_SCHED;
.LBB0_214:
	ds_read_b128 v[130:133], v155
	ds_read_b128 v[134:137], v155 offset:1024
	ds_read_b128 v[162:165], v155 offset:2048
	ds_read_b128 v[166:169], v155 offset:3072
	ds_read_b128 v[176:179], v170
	ds_read_b128 v[180:183], v170 offset:1024
	ds_read_b128 v[184:187], v170 offset:2048
	ds_read_b128 v[188:191], v170 offset:3072
	s_add_u32 s40, s2, 0xfff80080
	s_addc_u32 s41, s3, -1
	s_cmp_eq_u32 s60, 28
	s_cselect_b32 s43, s4, s41
	s_cselect_b32 s42, s31, s40
	s_cselect_b32 s41, s27, s59
	s_cselect_b32 s40, s33, s58
	v_lshl_add_u64 v[224:225], s[2:3], 0, v[156:157]
	s_add_i32 m0, s23, 0xc000
	ds_read_b128 v[192:195], v171
	ds_read_b128 v[196:199], v171 offset:1024
	ds_read_b128 v[200:203], v171 offset:2048
	ds_read_b128 v[204:207], v171 offset:3072
	ds_read_b128 v[208:211], v171 offset:4096
	ds_read_b128 v[212:215], v171 offset:5120
	ds_read_b128 v[216:219], v171 offset:6144
	ds_read_b128 v[220:223], v171 offset:7168
	global_load_lds_dwordx4 v[224:225], off
	v_lshl_add_u64 v[224:225], s[2:3], 0, v[158:159]
	s_add_i32 m0, s23, 0xe000
	s_nop 0
	global_load_lds_dwordx4 v[224:225], off
	s_waitcnt vmcnt(8)
	s_waitcnt lgkmcnt(0)
	s_barrier
	s_setprio 1
	s_waitcnt lgkmcnt(0)
	v_mfma_f32_16x16x32_bf16 v[126:129], v[130:133], v[192:195], v[126:129]
	v_mfma_f32_16x16x32_bf16 v[122:125], v[162:165], v[192:195], v[122:125]
	v_mfma_f32_16x16x32_bf16 v[118:121], v[130:133], v[200:203], v[118:121]
	v_mfma_f32_16x16x32_bf16 v[110:113], v[162:165], v[200:203], v[110:113]
	v_mfma_f32_16x16x32_bf16 v[102:105], v[130:133], v[208:211], v[102:105]
	v_mfma_f32_16x16x32_bf16 v[94:97], v[162:165], v[208:211], v[94:97]
	v_mfma_f32_16x16x32_bf16 v[86:89], v[130:133], v[216:219], v[86:89]
	v_mfma_f32_16x16x32_bf16 v[78:81], v[162:165], v[216:219], v[78:81]
	v_mfma_f32_16x16x32_bf16 v[126:129], v[134:137], v[196:199], v[126:129]
	v_mfma_f32_16x16x32_bf16 v[122:125], v[166:169], v[196:199], v[122:125]
	v_mfma_f32_16x16x32_bf16 v[118:121], v[134:137], v[204:207], v[118:121]
	v_mfma_f32_16x16x32_bf16 v[110:113], v[166:169], v[204:207], v[110:113]
	v_mfma_f32_16x16x32_bf16 v[102:105], v[134:137], v[212:215], v[102:105]
	v_mfma_f32_16x16x32_bf16 v[94:97], v[166:169], v[212:215], v[94:97]
	v_mfma_f32_16x16x32_bf16 v[86:89], v[134:137], v[220:223], v[86:89]
	v_mfma_f32_16x16x32_bf16 v[78:81], v[166:169], v[220:223], v[78:81]
	v_mfma_f32_16x16x32_bf16 v[114:117], v[176:179], v[192:195], v[114:117]
	v_mfma_f32_16x16x32_bf16 v[106:109], v[184:187], v[192:195], v[106:109]
	v_mfma_f32_16x16x32_bf16 v[98:101], v[176:179], v[200:203], v[98:101]
	v_mfma_f32_16x16x32_bf16 v[90:93], v[184:187], v[200:203], v[90:93]
	v_mfma_f32_16x16x32_bf16 v[82:85], v[176:179], v[208:211], v[82:85]
	v_mfma_f32_16x16x32_bf16 v[74:77], v[184:187], v[208:211], v[74:77]
	v_mfma_f32_16x16x32_bf16 v[70:73], v[176:179], v[216:219], v[70:73]
	v_mfma_f32_16x16x32_bf16 v[66:69], v[184:187], v[216:219], v[66:69]
	v_mfma_f32_16x16x32_bf16 v[114:117], v[180:183], v[196:199], v[114:117]
	v_mfma_f32_16x16x32_bf16 v[106:109], v[188:191], v[196:199], v[106:109]
	v_mfma_f32_16x16x32_bf16 v[98:101], v[180:183], v[204:207], v[98:101]
	v_mfma_f32_16x16x32_bf16 v[90:93], v[188:191], v[204:207], v[90:93]
	v_mfma_f32_16x16x32_bf16 v[82:85], v[180:183], v[212:215], v[82:85]
	v_mfma_f32_16x16x32_bf16 v[74:77], v[188:191], v[212:215], v[74:77]
	v_mfma_f32_16x16x32_bf16 v[70:73], v[180:183], v[220:223], v[70:73]
	v_mfma_f32_16x16x32_bf16 v[66:69], v[188:191], v[220:223], v[66:69]
	s_setprio 0
	s_barrier
	s_add_i32 s61, s51, s21
	v_lshl_add_u64 v[224:225], s[40:41], 0, v[140:141]
	s_mov_b32 m0, s61
	ds_read_b128 v[192:195], v171 offset:16384
	ds_read_b128 v[196:199], v171 offset:17408
	ds_read_b128 v[200:203], v171 offset:18432
	ds_read_b128 v[204:207], v171 offset:19456
	ds_read_b128 v[208:211], v171 offset:20480
	ds_read_b128 v[212:215], v171 offset:21504
	ds_read_b128 v[216:219], v171 offset:22528
	ds_read_b128 v[220:223], v171 offset:23552
	global_load_lds_dwordx4 v[224:225], off
	s_add_i32 m0, s61, 0x2000
	s_add_u32 s62, s40, 0x80000
	v_lshl_add_u64 v[226:227], s[40:41], 0, v[144:145]
	s_addc_u32 s63, s41, 0
	s_add_i32 s61, s52, s21
	global_load_lds_dwordx4 v[226:227], off
	v_lshl_add_u64 v[228:229], s[62:63], 0, v[140:141]
	s_mov_b32 m0, s61
	v_lshl_add_u64 v[230:231], s[42:43], 0, v[142:143]
	global_load_lds_dwordx4 v[228:229], off
	v_lshl_add_u64 v[228:229], s[62:63], 0, v[144:145]
	s_add_i32 m0, s61, 0x2000
	s_nop 0
	global_load_lds_dwordx4 v[228:229], off
	v_lshl_add_u64 v[228:229], s[42:43], 0, v[138:139]
	s_mov_b32 m0, s23
	s_nop 0
	global_load_lds_dwordx4 v[228:229], off
	s_mov_b32 m0, s25
	s_nop 0
	global_load_lds_dwordx4 v[230:231], off
	s_waitcnt vmcnt(8)
	s_waitcnt lgkmcnt(0)
	s_barrier
; #define PG8_STAGE(bufoff, gbase, voff) do { _Pragma("unroll") for (int _i = 0; _i < 2; ++_i) \
;         __builtin_amdgcn_global_load_lds((const unsigned*)((const char*)(gbase) + (voff)[_i]), (PG8_LAS unsigned*)(lds + (bufoff) + ldsw + _i * 8192), 16, 0, 0); } while (0)
; #define PG8_LDA(dst, b, h) do { _Pragma("unroll") for (int m = 0; m < 4; ++m) _Pragma("unroll") for (int k = 0; k < 2; ++k) dst[m][k] = *(const PG8_LAS bf16x8*)(lds + PG8_SA(b, h) + aoff + m * 2048 + k * 1024); } while (0)
; #define PG8_LDB(dst, b, h) do { _Pragma("unroll") for (int n = 0; n < 2; ++n) _Pragma("unroll") for (int k = 0; k < 2; ++k) dst[n][k] = *(const PG8_LAS bf16x8*)(lds + PG8_SB(b, h) + boff + n * 2048 + k * 1024); } while (0)
; #define PG8_MMA(ai, bj, At, Bt) do { __builtin_amdgcn_s_setprio(1); _Pragma("unroll") for (int m = 0; m < 4; ++m) _Pragma("unroll") for (int n = 0; n < 2; ++n) _Pragma("unroll") for (int k = 0; k < 2; ++k) \
;         acc[ai][bj][m][n] = __builtin_amdgcn_mfma_f32_16x16x32_bf16(Bt[n][k], At[m][k], acc[ai][bj][m][n], 0, 0, 0); __builtin_amdgcn_s_setprio(0); } while (0)
; #define PG8_WAIT_V(n) asm volatile("s_waitcnt vmcnt(" #n ")" ::: "memory")
; #define PG8_WAIT_L(n) asm volatile("s_waitcnt lgkmcnt(" #n ")" ::: "memory")
; #define PG8_BAR __builtin_amdgcn_s_barrier()
; #define PG8_SCHED __builtin_amdgcn_sched_barrier(0)
; template <class Epi, class Sched>
; __device__ __forceinline__ void gemm_phase(PG8_LAS unsigned char* lds, const Gemm g, const Sched& S, const Epi& E) {
;     ...
;             PG8_WAIT_V(8); PG8_WAIT_L(0); PG8_BAR; PG8_MMA(1, 0, At, B0); PG8_MMA(1, 1, At, B1); PG8_BAR; PG8_SCHED;
;             PG8_LDB(B0, 1, 0); PG8_LDB(B1, 1, 1); PG8_SCHED; PG8_LDA(At, 1, 0); PG8_STAGE(PG8_SA(0, 1), a2 + hstepA, voffA);
;             PG8_WAIT_V(8); PG8_WAIT_L(0); PG8_BAR; PG8_MMA(0, 0, At, B0); PG8_MMA(0, 1, At, B1); PG8_BAR; PG8_SCHED;
;             PG8_LDA(At, 1, 1); PG8_STAGE(PG8_SB(1, 0), b3, voffB); PG8_STAGE(PG8_SB(1, 1), b3 + hstepB, voffB); PG8_STAGE(PG8_SA(1, 0), a3, voffA);
	s_setprio 1
	s_waitcnt lgkmcnt(0)
	v_mfma_f32_16x16x32_bf16 v[62:65], v[130:133], v[192:195], v[62:65]
	v_mfma_f32_16x16x32_bf16 v[58:61], v[162:165], v[192:195], v[58:61]
	v_mfma_f32_16x16x32_bf16 v[54:57], v[130:133], v[200:203], v[54:57]
	v_mfma_f32_16x16x32_bf16 v[46:49], v[162:165], v[200:203], v[46:49]
	v_mfma_f32_16x16x32_bf16 v[38:41], v[130:133], v[208:211], v[38:41]
	v_mfma_f32_16x16x32_bf16 v[30:33], v[162:165], v[208:211], v[30:33]
	v_mfma_f32_16x16x32_bf16 v[22:25], v[130:133], v[216:219], v[22:25]
	v_mfma_f32_16x16x32_bf16 v[14:17], v[162:165], v[216:219], v[14:17]
	v_mfma_f32_16x16x32_bf16 v[62:65], v[134:137], v[196:199], v[62:65]
	v_mfma_f32_16x16x32_bf16 v[58:61], v[166:169], v[196:199], v[58:61]
	v_mfma_f32_16x16x32_bf16 v[54:57], v[134:137], v[204:207], v[54:57]
	v_mfma_f32_16x16x32_bf16 v[46:49], v[166:169], v[204:207], v[46:49]
	v_mfma_f32_16x16x32_bf16 v[38:41], v[134:137], v[212:215], v[38:41]
	v_mfma_f32_16x16x32_bf16 v[30:33], v[166:169], v[212:215], v[30:33]
	v_mfma_f32_16x16x32_bf16 v[22:25], v[134:137], v[220:223], v[22:25]
	v_mfma_f32_16x16x32_bf16 v[14:17], v[166:169], v[220:223], v[14:17]
	v_mfma_f32_16x16x32_bf16 v[50:53], v[176:179], v[192:195], v[50:53]
	v_mfma_f32_16x16x32_bf16 v[42:45], v[184:187], v[192:195], v[42:45]
	v_mfma_f32_16x16x32_bf16 v[34:37], v[176:179], v[200:203], v[34:37]
	v_mfma_f32_16x16x32_bf16 v[26:29], v[184:187], v[200:203], v[26:29]
	v_mfma_f32_16x16x32_bf16 v[18:21], v[176:179], v[208:211], v[18:21]
	v_mfma_f32_16x16x32_bf16 v[10:13], v[184:187], v[208:211], v[10:13]
	v_mfma_f32_16x16x32_bf16 v[6:9], v[176:179], v[216:219], v[6:9]
	v_mfma_f32_16x16x32_bf16 v[2:5], v[184:187], v[216:219], v[2:5]
	v_mfma_f32_16x16x32_bf16 v[50:53], v[180:183], v[196:199], v[50:53]
	v_mfma_f32_16x16x32_bf16 v[42:45], v[188:191], v[196:199], v[42:45]
	v_mfma_f32_16x16x32_bf16 v[34:37], v[180:183], v[204:207], v[34:37]
	v_mfma_f32_16x16x32_bf16 v[26:29], v[188:191], v[204:207], v[26:29]
	v_mfma_f32_16x16x32_bf16 v[18:21], v[180:183], v[212:215], v[18:21]
	v_mfma_f32_16x16x32_bf16 v[10:13], v[188:191], v[212:215], v[10:13]
	v_mfma_f32_16x16x32_bf16 v[6:9], v[180:183], v[220:223], v[6:9]
	v_mfma_f32_16x16x32_bf16 v[2:5], v[188:191], v[220:223], v[2:5]
	s_setprio 0
	s_barrier
	s_add_i32 s61, 0, 0x18000
	v_add_u32_e32 v146, s61, v149
	s_add_i32 s62, 0, 0x1c000
	ds_read_b128 v[130:133], v146
	ds_read_b128 v[134:137], v146 offset:1024
	ds_read_b128 v[162:165], v146 offset:2048
	ds_read_b128 v[166:169], v146 offset:3072
	v_add_u32_e32 v146, s62, v149
	ds_read_b128 v[176:179], v146
	ds_read_b128 v[180:183], v146 offset:1024
	ds_read_b128 v[184:187], v146 offset:2048
	ds_read_b128 v[188:191], v146 offset:3072
	s_add_u32 s42, s42, 0x80000
	s_addc_u32 s43, s43, 0
	s_mov_b32 m0, s29
	v_lshl_add_u64 v[232:233], s[42:43], 0, v[138:139]
	ds_read_b128 v[192:195], v171 offset:32768
	ds_read_b128 v[196:199], v171 offset:33792
	ds_read_b128 v[200:203], v171 offset:34816
	ds_read_b128 v[204:207], v171 offset:35840
	ds_read_b128 v[208:211], v171 offset:36864
	ds_read_b128 v[212:215], v171 offset:37888
	ds_read_b128 v[216:219], v171 offset:38912
	ds_read_b128 v[220:223], v171 offset:39936
	global_load_lds_dwordx4 v[232:233], off
	v_lshl_add_u64 v[232:233], s[42:43], 0, v[142:143]
	s_mov_b32 m0, s44
	s_nop 0
	global_load_lds_dwordx4 v[232:233], off
	s_waitcnt vmcnt(8)
	s_waitcnt lgkmcnt(0)
	s_barrier
	s_setprio 1
	s_waitcnt lgkmcnt(0)
	v_mfma_f32_16x16x32_bf16 v[126:129], v[130:133], v[192:195], v[126:129]
	v_mfma_f32_16x16x32_bf16 v[122:125], v[162:165], v[192:195], v[122:125]
	v_mfma_f32_16x16x32_bf16 v[118:121], v[130:133], v[200:203], v[118:121]
	v_mfma_f32_16x16x32_bf16 v[110:113], v[162:165], v[200:203], v[110:113]
	v_mfma_f32_16x16x32_bf16 v[102:105], v[130:133], v[208:211], v[102:105]
	v_mfma_f32_16x16x32_bf16 v[94:97], v[162:165], v[208:211], v[94:97]
	v_mfma_f32_16x16x32_bf16 v[86:89], v[130:133], v[216:219], v[86:89]
	v_mfma_f32_16x16x32_bf16 v[78:81], v[162:165], v[216:219], v[78:81]
	v_mfma_f32_16x16x32_bf16 v[126:129], v[134:137], v[196:199], v[126:129]
	v_mfma_f32_16x16x32_bf16 v[122:125], v[166:169], v[196:199], v[122:125]
	v_mfma_f32_16x16x32_bf16 v[118:121], v[134:137], v[204:207], v[118:121]
	v_mfma_f32_16x16x32_bf16 v[110:113], v[166:169], v[204:207], v[110:113]
	v_mfma_f32_16x16x32_bf16 v[102:105], v[134:137], v[212:215], v[102:105]
	v_mfma_f32_16x16x32_bf16 v[94:97], v[166:169], v[212:215], v[94:97]
	v_mfma_f32_16x16x32_bf16 v[86:89], v[134:137], v[220:223], v[86:89]
	v_mfma_f32_16x16x32_bf16 v[78:81], v[166:169], v[220:223], v[78:81]
	v_mfma_f32_16x16x32_bf16 v[114:117], v[176:179], v[192:195], v[114:117]
	v_mfma_f32_16x16x32_bf16 v[106:109], v[184:187], v[192:195], v[106:109]
	v_mfma_f32_16x16x32_bf16 v[98:101], v[176:179], v[200:203], v[98:101]
	v_mfma_f32_16x16x32_bf16 v[90:93], v[184:187], v[200:203], v[90:93]
	v_mfma_f32_16x16x32_bf16 v[82:85], v[176:179], v[208:211], v[82:85]
	v_mfma_f32_16x16x32_bf16 v[74:77], v[184:187], v[208:211], v[74:77]
	v_mfma_f32_16x16x32_bf16 v[70:73], v[176:179], v[216:219], v[70:73]
	v_mfma_f32_16x16x32_bf16 v[66:69], v[184:187], v[216:219], v[66:69]
	v_mfma_f32_16x16x32_bf16 v[114:117], v[180:183], v[196:199], v[114:117]
	v_mfma_f32_16x16x32_bf16 v[106:109], v[188:191], v[196:199], v[106:109]
	v_mfma_f32_16x16x32_bf16 v[98:101], v[180:183], v[204:207], v[98:101]
	v_mfma_f32_16x16x32_bf16 v[90:93], v[188:191], v[204:207], v[90:93]
	v_mfma_f32_16x16x32_bf16 v[82:85], v[180:183], v[212:215], v[82:85]
	v_mfma_f32_16x16x32_bf16 v[74:77], v[188:191], v[212:215], v[74:77]
	v_mfma_f32_16x16x32_bf16 v[70:73], v[180:183], v[220:223], v[70:73]
	v_mfma_f32_16x16x32_bf16 v[66:69], v[188:191], v[220:223], v[66:69]
	s_setprio 0
	s_barrier
; #define PG8_STAGE(bufoff, gbase, voff) do { _Pragma("unroll") for (int _i = 0; _i < 2; ++_i) \
;         __builtin_amdgcn_global_load_lds((const unsigned*)((const char*)(gbase) + (voff)[_i]), (PG8_LAS unsigned*)(lds + (bufoff) + ldsw + _i * 8192), 16, 0, 0); } while (0)
; #define PG8_LDA(dst, b, h) do { _Pragma("unroll") for (int m = 0; m < 4; ++m) _Pragma("unroll") for (int k = 0; k < 2; ++k) dst[m][k] = *(const PG8_LAS bf16x8*)(lds + PG8_SA(b, h) + aoff + m * 2048 + k * 1024); } while (0)
; #define PG8_MMA(ai, bj, At, Bt) do { __builtin_amdgcn_s_setprio(1); _Pragma("unroll") for (int m = 0; m < 4; ++m) _Pragma("unroll") for (int n = 0; n < 2; ++n) _Pragma("unroll") for (int k = 0; k < 2; ++k) \
;         acc[ai][bj][m][n] = __builtin_amdgcn_mfma_f32_16x16x32_bf16(Bt[n][k], At[m][k], acc[ai][bj][m][n], 0, 0, 0); __builtin_amdgcn_s_setprio(0); } while (0)
; #define PG8_WAIT_V(n) asm volatile("s_waitcnt vmcnt(" #n ")" ::: "memory")
; #define PG8_WAIT_L(n) asm volatile("s_waitcnt lgkmcnt(" #n ")" ::: "memory")
; #define PG8_BAR __builtin_amdgcn_s_barrier()
; #define PG8_SCHED __builtin_amdgcn_sched_barrier(0)
; template <class Epi, class Sched>
; __device__ __forceinline__ void gemm_phase(PG8_LAS unsigned char* lds, const Gemm g, const Sched& S, const Epi& E) {
;     ...
;             PG8_LDA(At, 1, 1); PG8_STAGE(PG8_SB(1, 0), b3, voffB); PG8_STAGE(PG8_SB(1, 1), b3 + hstepB, voffB); PG8_STAGE(PG8_SA(1, 0), a3, voffA);
;             PG8_WAIT_V(8); PG8_WAIT_L(0); PG8_BAR; PG8_MMA(1, 0, At, B0); PG8_MMA(1, 1, At, B1); PG8_BAR; PG8_SCHED;
;         }
	s_add_i32 s42, s61, s21
	v_lshl_add_u64 v[224:225], v[224:225], 0, s[10:11]
	s_mov_b32 m0, s42
	ds_read_b128 v[192:195], v171 offset:49152
	ds_read_b128 v[196:199], v171 offset:50176
	ds_read_b128 v[200:203], v171 offset:51200
	ds_read_b128 v[204:207], v171 offset:52224
	ds_read_b128 v[208:211], v171 offset:53248
	ds_read_b128 v[212:215], v171 offset:54272
	ds_read_b128 v[216:219], v171 offset:55296
	ds_read_b128 v[220:223], v171 offset:56320
	global_load_lds_dwordx4 v[224:225], off
	s_add_i32 m0, s42, 0x2000
	s_add_u32 s40, s40, 0x80080
	v_lshl_add_u64 v[224:225], v[226:227], 0, s[10:11]
	s_addc_u32 s41, s41, 0
	s_add_i32 s42, s62, s21
	global_load_lds_dwordx4 v[224:225], off
	v_lshl_add_u64 v[224:225], s[40:41], 0, v[140:141]
	s_mov_b32 m0, s42
	s_nop 0
	global_load_lds_dwordx4 v[224:225], off
	v_lshl_add_u64 v[224:225], s[40:41], 0, v[144:145]
	s_add_i32 m0, s42, 0x2000
	s_nop 0
	global_load_lds_dwordx4 v[224:225], off
	v_lshl_add_u64 v[224:225], v[228:229], 0, s[10:11]
	s_mov_b32 m0, s47
	s_nop 0
	global_load_lds_dwordx4 v[224:225], off
	v_lshl_add_u64 v[224:225], v[230:231], 0, s[10:11]
	s_mov_b32 m0, s48
	s_nop 0
	global_load_lds_dwordx4 v[224:225], off
	s_waitcnt vmcnt(8)
	s_waitcnt lgkmcnt(0)
	s_barrier
	s_setprio 1
	s_waitcnt lgkmcnt(0)
	v_mfma_f32_16x16x32_bf16 v[62:65], v[130:133], v[192:195], v[62:65]
	v_mfma_f32_16x16x32_bf16 v[58:61], v[162:165], v[192:195], v[58:61]
	v_mfma_f32_16x16x32_bf16 v[54:57], v[130:133], v[200:203], v[54:57]
	v_mfma_f32_16x16x32_bf16 v[46:49], v[162:165], v[200:203], v[46:49]
	v_mfma_f32_16x16x32_bf16 v[38:41], v[130:133], v[208:211], v[38:41]
	v_mfma_f32_16x16x32_bf16 v[30:33], v[162:165], v[208:211], v[30:33]
	v_mfma_f32_16x16x32_bf16 v[22:25], v[130:133], v[216:219], v[22:25]
	v_mfma_f32_16x16x32_bf16 v[14:17], v[162:165], v[216:219], v[14:17]
	v_mfma_f32_16x16x32_bf16 v[62:65], v[134:137], v[196:199], v[62:65]
	v_mfma_f32_16x16x32_bf16 v[58:61], v[166:169], v[196:199], v[58:61]
	v_mfma_f32_16x16x32_bf16 v[54:57], v[134:137], v[204:207], v[54:57]
	v_mfma_f32_16x16x32_bf16 v[46:49], v[166:169], v[204:207], v[46:49]
	v_mfma_f32_16x16x32_bf16 v[38:41], v[134:137], v[212:215], v[38:41]
	v_mfma_f32_16x16x32_bf16 v[30:33], v[166:169], v[212:215], v[30:33]
	v_mfma_f32_16x16x32_bf16 v[22:25], v[134:137], v[220:223], v[22:25]
	v_mfma_f32_16x16x32_bf16 v[14:17], v[166:169], v[220:223], v[14:17]
	v_mfma_f32_16x16x32_bf16 v[50:53], v[176:179], v[192:195], v[50:53]
	v_mfma_f32_16x16x32_bf16 v[42:45], v[184:187], v[192:195], v[42:45]
	v_mfma_f32_16x16x32_bf16 v[34:37], v[176:179], v[200:203], v[34:37]
	v_mfma_f32_16x16x32_bf16 v[26:29], v[184:187], v[200:203], v[26:29]
	v_mfma_f32_16x16x32_bf16 v[18:21], v[176:179], v[208:211], v[18:21]
	v_mfma_f32_16x16x32_bf16 v[10:13], v[184:187], v[208:211], v[10:13]
	v_mfma_f32_16x16x32_bf16 v[6:9], v[176:179], v[216:219], v[6:9]
	v_mfma_f32_16x16x32_bf16 v[2:5], v[184:187], v[216:219], v[2:5]
	v_mfma_f32_16x16x32_bf16 v[50:53], v[180:183], v[196:199], v[50:53]
	v_mfma_f32_16x16x32_bf16 v[42:45], v[188:191], v[196:199], v[42:45]
	v_mfma_f32_16x16x32_bf16 v[34:37], v[180:183], v[204:207], v[34:37]
	v_mfma_f32_16x16x32_bf16 v[26:29], v[188:191], v[204:207], v[26:29]
	v_mfma_f32_16x16x32_bf16 v[18:21], v[180:183], v[212:215], v[18:21]
	v_mfma_f32_16x16x32_bf16 v[10:13], v[188:191], v[212:215], v[10:13]
	v_mfma_f32_16x16x32_bf16 v[6:9], v[180:183], v[220:223], v[6:9]
	v_mfma_f32_16x16x32_bf16 v[2:5], v[188:191], v[220:223], v[2:5]
	s_setprio 0
	s_barrier
	s_add_i32 s60, s60, 2
	s_add_u32 s2, s2, 0x100
	s_addc_u32 s3, s3, 0
	s_add_u32 s58, s58, 0x100
	s_addc_u32 s59, s59, 0
	s_cmp_gt_u32 s60, 29
	s_cbranch_scc0 .LBB0_214
	s_and_b64 vcc, exec, s[12:13]
	s_cbranch_vccz .LBB0_217
	s_barrier

; #define PG8_STAGE(bufoff, gbase, voff) do { _Pragma("unroll") for (int _i = 0; _i < 2; ++_i) \
;         __builtin_amdgcn_global_load_lds((const unsigned*)((const char*)(gbase) + (voff)[_i]), (PG8_LAS unsigned*)(lds + (bufoff) + ldsw + _i * 8192), 16, 0, 0); } while (0)
; #define PG8_LDA(dst, b, h) do { _Pragma("unroll") for (int m = 0; m < 4; ++m) _Pragma("unroll") for (int k = 0; k < 2; ++k) dst[m][k] = *(const PG8_LAS bf16x8*)(lds + PG8_SA(b, h) + aoff + m * 2048 + k * 1024); } while (0)
; #define PG8_LDB(dst, b, h) do { _Pragma("unroll") for (int n = 0; n < 2; ++n) _Pragma("unroll") for (int k = 0; k < 2; ++k) dst[n][k] = *(const PG8_LAS bf16x8*)(lds + PG8_SB(b, h) + boff + n * 2048 + k * 1024); } while (0)
; #define PG8_MMA(ai, bj, At, Bt) do { __builtin_amdgcn_s_setprio(1); _Pragma("unroll") for (int m = 0; m < 4; ++m) _Pragma("unroll") for (int n = 0; n < 2; ++n) _Pragma("unroll") for (int k = 0; k < 2; ++k) \
;         acc[ai][bj][m][n] = __builtin_amdgcn_mfma_f32_16x16x32_bf16(Bt[n][k], At[m][k], acc[ai][bj][m][n], 0, 0, 0); __builtin_amdgcn_s_setprio(0); } while (0)
; #define PG8_WAIT_V(n) asm volatile("s_waitcnt vmcnt(" #n ")" ::: "memory")
; #define PG8_WAIT_L(n) asm volatile("s_waitcnt lgkmcnt(" #n ")" ::: "memory")
; #define PG8_BAR __builtin_amdgcn_s_barrier()
; #define PG8_SCHED __builtin_amdgcn_sched_barrier(0)
; template <class Epi, class Sched>
; __device__ __forceinline__ void gemm_phase(PG8_LAS unsigned char* lds, const Gemm g, const Sched& S, const Epi& E) {
;     ...
;             PG8_LDB(B0, 0, 0); PG8_LDB(B1, 0, 1); PG8_SCHED; PG8_LDA(At, 0, 0); PG8_STAGE(PG8_SA(1, 1), a1 + hstepA, voffA);
;             PG8_WAIT_V(8); PG8_WAIT_L(0); PG8_BAR; PG8_MMA(0, 0, At, B0); PG8_MMA(0, 1, At, B1); PG8_BAR; PG8_SCHED;
;             PG8_LDA(At, 0, 1); PG8_STAGE(PG8_SB(0, 0), b2, voffB); PG8_STAGE(PG8_SB(0, 1), b2 + hstepB, voffB); PG8_STAGE(PG8_SA(0, 0), a2, voffA);
;             PG8_WAIT_V(8); PG8_WAIT_L(0); PG8_BAR; PG8_MMA(1, 0, At, B0); PG8_MMA(1, 1, At, B1); PG8_BAR; PG8_SCHED;
.LBB0_611:
	v_add_u32_e32 v3, s66, v165
	ds_read_b128 v[134:137], v3
	ds_read_b128 v[138:141], v3 offset:1024
	ds_read_b128 v[142:145], v3 offset:2048
	ds_read_b128 v[146:149], v3 offset:3072
	v_add_u32_e32 v3, s67, v165
	ds_read_b128 v[150:153], v3
	ds_read_b128 v[172:175], v3 offset:1024
	ds_read_b128 v[176:179], v3 offset:2048
	ds_read_b128 v[184:187], v3 offset:3072
	s_add_u32 s44, s46, 0xfff80080
	s_addc_u32 s45, s47, -1
	s_cmp_eq_u32 s74, 28
	s_cselect_b32 s49, s37, s45
	s_cselect_b32 s48, s70, s44
	s_cselect_b32 s45, s35, s73
	s_cselect_b32 s44, s71, s72
	v_lshl_add_u64 v[4:5], s[46:47], 0, v[166:167]
	s_add_i32 m0, s56, 0xc000
	ds_read_b128 v[188:191], v182
	ds_read_b128 v[192:195], v182 offset:1024
	ds_read_b128 v[196:199], v182 offset:2048
	ds_read_b128 v[200:203], v182 offset:3072
	ds_read_b128 v[204:207], v182 offset:4096
	ds_read_b128 v[208:211], v182 offset:5120
	ds_read_b128 v[212:215], v182 offset:6144
	ds_read_b128 v[216:219], v182 offset:7168
	global_load_lds_dwordx4 v[4:5], off
	v_lshl_add_u64 v[4:5], s[46:47], 0, v[168:169]
	s_add_i32 m0, s56, 0xe000
	s_nop 0
	global_load_lds_dwordx4 v[4:5], off
	s_waitcnt vmcnt(8)
	s_waitcnt lgkmcnt(0)
	s_barrier
	s_setprio 1
	s_waitcnt lgkmcnt(0)
	v_mfma_f32_16x16x32_bf16 v[130:133], v[134:137], v[188:191], v[130:133]
	v_mfma_f32_16x16x32_bf16 v[126:129], v[142:145], v[188:191], v[126:129]
	v_mfma_f32_16x16x32_bf16 v[122:125], v[134:137], v[196:199], v[122:125]
	v_mfma_f32_16x16x32_bf16 v[118:121], v[142:145], v[196:199], v[118:121]
	v_mfma_f32_16x16x32_bf16 v[114:117], v[134:137], v[204:207], v[114:117]
	v_mfma_f32_16x16x32_bf16 v[110:113], v[142:145], v[204:207], v[110:113]
	v_mfma_f32_16x16x32_bf16 v[106:109], v[134:137], v[212:215], v[106:109]
	v_mfma_f32_16x16x32_bf16 v[102:105], v[142:145], v[212:215], v[102:105]
	v_mfma_f32_16x16x32_bf16 v[130:133], v[138:141], v[192:195], v[130:133]
	v_mfma_f32_16x16x32_bf16 v[126:129], v[146:149], v[192:195], v[126:129]
	v_mfma_f32_16x16x32_bf16 v[122:125], v[138:141], v[200:203], v[122:125]
	v_mfma_f32_16x16x32_bf16 v[118:121], v[146:149], v[200:203], v[118:121]
	v_mfma_f32_16x16x32_bf16 v[114:117], v[138:141], v[208:211], v[114:117]
	v_mfma_f32_16x16x32_bf16 v[110:113], v[146:149], v[208:211], v[110:113]
	v_mfma_f32_16x16x32_bf16 v[106:109], v[138:141], v[216:219], v[106:109]
	v_mfma_f32_16x16x32_bf16 v[102:105], v[146:149], v[216:219], v[102:105]
	v_mfma_f32_16x16x32_bf16 v[98:101], v[150:153], v[188:191], v[98:101]
	v_mfma_f32_16x16x32_bf16 v[94:97], v[176:179], v[188:191], v[94:97]
	v_mfma_f32_16x16x32_bf16 v[90:93], v[150:153], v[196:199], v[90:93]
	v_mfma_f32_16x16x32_bf16 v[86:89], v[176:179], v[196:199], v[86:89]
	v_mfma_f32_16x16x32_bf16 v[82:85], v[150:153], v[204:207], v[82:85]
	v_mfma_f32_16x16x32_bf16 v[78:81], v[176:179], v[204:207], v[78:81]
	v_mfma_f32_16x16x32_bf16 v[74:77], v[150:153], v[212:215], v[74:77]
	v_mfma_f32_16x16x32_bf16 v[70:73], v[176:179], v[212:215], v[70:73]
	v_mfma_f32_16x16x32_bf16 v[98:101], v[172:175], v[192:195], v[98:101]
	v_mfma_f32_16x16x32_bf16 v[94:97], v[184:187], v[192:195], v[94:97]
	v_mfma_f32_16x16x32_bf16 v[90:93], v[172:175], v[200:203], v[90:93]
	v_mfma_f32_16x16x32_bf16 v[86:89], v[184:187], v[200:203], v[86:89]
	v_mfma_f32_16x16x32_bf16 v[82:85], v[172:175], v[208:211], v[82:85]
	v_mfma_f32_16x16x32_bf16 v[78:81], v[184:187], v[208:211], v[78:81]
	v_mfma_f32_16x16x32_bf16 v[74:77], v[172:175], v[216:219], v[74:77]
	v_mfma_f32_16x16x32_bf16 v[70:73], v[184:187], v[216:219], v[70:73]
	s_setprio 0
	s_barrier
	s_add_i32 s75, s66, s55
	v_lshl_add_u64 v[180:181], s[44:45], 0, v[158:159]
	s_mov_b32 m0, s75
	ds_read_b128 v[188:191], v182 offset:16384
	ds_read_b128 v[192:195], v182 offset:17408
	ds_read_b128 v[196:199], v182 offset:18432
	ds_read_b128 v[200:203], v182 offset:19456
	ds_read_b128 v[204:207], v182 offset:20480
	ds_read_b128 v[208:211], v182 offset:21504
	ds_read_b128 v[212:215], v182 offset:22528
	ds_read_b128 v[216:219], v182 offset:23552
	global_load_lds_dwordx4 v[180:181], off
	s_add_i32 m0, s75, 0x2000
	s_add_u32 s76, s44, 0x80000
	v_lshl_add_u64 v[220:221], s[44:45], 0, v[162:163]
	s_addc_u32 s77, s45, 0
	s_add_i32 s75, s67, s55
	global_load_lds_dwordx4 v[220:221], off
	v_lshl_add_u64 v[4:5], s[76:77], 0, v[158:159]
	s_mov_b32 m0, s75
	v_lshl_add_u64 v[222:223], s[48:49], 0, v[156:157]
	global_load_lds_dwordx4 v[4:5], off
	v_lshl_add_u64 v[4:5], s[76:77], 0, v[162:163]
	s_add_i32 m0, s75, 0x2000
	v_lshl_add_u64 v[224:225], s[48:49], 0, v[160:161]
	global_load_lds_dwordx4 v[4:5], off
	s_mov_b32 m0, s56
	s_nop 0
	global_load_lds_dwordx4 v[222:223], off
	s_mov_b32 m0, s57
	s_nop 0
	global_load_lds_dwordx4 v[224:225], off
	s_waitcnt vmcnt(8)
	s_waitcnt lgkmcnt(0)
	s_barrier
; #define PG8_STAGE(bufoff, gbase, voff) do { _Pragma("unroll") for (int _i = 0; _i < 2; ++_i) \
;         __builtin_amdgcn_global_load_lds((const unsigned*)((const char*)(gbase) + (voff)[_i]), (PG8_LAS unsigned*)(lds + (bufoff) + ldsw + _i * 8192), 16, 0, 0); } while (0)
; #define PG8_LDA(dst, b, h) do { _Pragma("unroll") for (int m = 0; m < 4; ++m) _Pragma("unroll") for (int k = 0; k < 2; ++k) dst[m][k] = *(const PG8_LAS bf16x8*)(lds + PG8_SA(b, h) + aoff + m * 2048 + k * 1024); } while (0)
; #define PG8_LDB(dst, b, h) do { _Pragma("unroll") for (int n = 0; n < 2; ++n) _Pragma("unroll") for (int k = 0; k < 2; ++k) dst[n][k] = *(const PG8_LAS bf16x8*)(lds + PG8_SB(b, h) + boff + n * 2048 + k * 1024); } while (0)
; #define PG8_MMA(ai, bj, At, Bt) do { __builtin_amdgcn_s_setprio(1); _Pragma("unroll") for (int m = 0; m < 4; ++m) _Pragma("unroll") for (int n = 0; n < 2; ++n) _Pragma("unroll") for (int k = 0; k < 2; ++k) \
;         acc[ai][bj][m][n] = __builtin_amdgcn_mfma_f32_16x16x32_bf16(Bt[n][k], At[m][k], acc[ai][bj][m][n], 0, 0, 0); __builtin_amdgcn_s_setprio(0); } while (0)
; #define PG8_WAIT_V(n) asm volatile("s_waitcnt vmcnt(" #n ")" ::: "memory")
; #define PG8_WAIT_L(n) asm volatile("s_waitcnt lgkmcnt(" #n ")" ::: "memory")
; #define PG8_BAR __builtin_amdgcn_s_barrier()
; #define PG8_SCHED __builtin_amdgcn_sched_barrier(0)
; template <class Epi, class Sched>
; __device__ __forceinline__ void gemm_phase(PG8_LAS unsigned char* lds, const Gemm g, const Sched& S, const Epi& E) {
;     ...
;             PG8_WAIT_V(8); PG8_WAIT_L(0); PG8_BAR; PG8_MMA(1, 0, At, B0); PG8_MMA(1, 1, At, B1); PG8_BAR; PG8_SCHED;
;             PG8_LDB(B0, 1, 0); PG8_LDB(B1, 1, 1); PG8_SCHED; PG8_LDA(At, 1, 0); PG8_STAGE(PG8_SA(0, 1), a2 + hstepA, voffA);
;             PG8_WAIT_V(8); PG8_WAIT_L(0); PG8_BAR; PG8_MMA(0, 0, At, B0); PG8_MMA(0, 1, At, B1); PG8_BAR; PG8_SCHED;
;             PG8_LDA(At, 1, 1); PG8_STAGE(PG8_SB(1, 0), b3, voffB); PG8_STAGE(PG8_SB(1, 1), b3 + hstepB, voffB); PG8_STAGE(PG8_SA(1, 0), a3, voffA);
	s_setprio 1
	s_waitcnt lgkmcnt(0)
	v_mfma_f32_16x16x32_bf16 v[66:69], v[134:137], v[188:191], v[66:69]
	v_mfma_f32_16x16x32_bf16 v[62:65], v[142:145], v[188:191], v[62:65]
	v_mfma_f32_16x16x32_bf16 v[58:61], v[134:137], v[196:199], v[58:61]
	v_mfma_f32_16x16x32_bf16 v[54:57], v[142:145], v[196:199], v[54:57]
	v_mfma_f32_16x16x32_bf16 v[50:53], v[134:137], v[204:207], v[50:53]
	v_mfma_f32_16x16x32_bf16 v[46:49], v[142:145], v[204:207], v[46:49]
	v_mfma_f32_16x16x32_bf16 v[42:45], v[134:137], v[212:215], v[42:45]
	v_mfma_f32_16x16x32_bf16 v[38:41], v[142:145], v[212:215], v[38:41]
	v_mfma_f32_16x16x32_bf16 v[66:69], v[138:141], v[192:195], v[66:69]
	v_mfma_f32_16x16x32_bf16 v[62:65], v[146:149], v[192:195], v[62:65]
	v_mfma_f32_16x16x32_bf16 v[58:61], v[138:141], v[200:203], v[58:61]
	v_mfma_f32_16x16x32_bf16 v[54:57], v[146:149], v[200:203], v[54:57]
	v_mfma_f32_16x16x32_bf16 v[50:53], v[138:141], v[208:211], v[50:53]
	v_mfma_f32_16x16x32_bf16 v[46:49], v[146:149], v[208:211], v[46:49]
	v_mfma_f32_16x16x32_bf16 v[42:45], v[138:141], v[216:219], v[42:45]
	v_mfma_f32_16x16x32_bf16 v[38:41], v[146:149], v[216:219], v[38:41]
	v_mfma_f32_16x16x32_bf16 v[34:37], v[150:153], v[188:191], v[34:37]
	v_mfma_f32_16x16x32_bf16 v[30:33], v[176:179], v[188:191], v[30:33]
	v_mfma_f32_16x16x32_bf16 v[26:29], v[150:153], v[196:199], v[26:29]
	v_mfma_f32_16x16x32_bf16 v[22:25], v[176:179], v[196:199], v[22:25]
	v_mfma_f32_16x16x32_bf16 v[18:21], v[150:153], v[204:207], v[18:21]
	v_mfma_f32_16x16x32_bf16 v[14:17], v[176:179], v[204:207], v[14:17]
	v_mfma_f32_16x16x32_bf16 v[10:13], v[150:153], v[212:215], v[10:13]
	v_mfma_f32_16x16x32_bf16 v[4:7], v[176:179], v[212:215], v[6:9]
	v_mfma_f32_16x16x32_bf16 v[34:37], v[172:175], v[192:195], v[34:37]
	v_mfma_f32_16x16x32_bf16 v[30:33], v[184:187], v[192:195], v[30:33]
	v_mfma_f32_16x16x32_bf16 v[26:29], v[172:175], v[200:203], v[26:29]
	v_mfma_f32_16x16x32_bf16 v[22:25], v[184:187], v[200:203], v[22:25]
	v_mfma_f32_16x16x32_bf16 v[18:21], v[172:175], v[208:211], v[18:21]
	v_mfma_f32_16x16x32_bf16 v[14:17], v[184:187], v[208:211], v[14:17]
	v_mfma_f32_16x16x32_bf16 v[10:13], v[172:175], v[216:219], v[10:13]
	v_mfma_f32_16x16x32_bf16 v[4:7], v[184:187], v[216:219], v[4:7]
	s_setprio 0
	s_barrier
	s_add_i32 s75, 0, 0x18000
	v_add_u32_e32 v3, s75, v165
	s_add_i32 s76, 0, 0x1c000
	ds_read_b128 v[134:137], v3
	ds_read_b128 v[138:141], v3 offset:1024
	ds_read_b128 v[142:145], v3 offset:2048
	ds_read_b128 v[146:149], v3 offset:3072
	v_add_u32_e32 v3, s76, v165
	ds_read_b128 v[150:153], v3
	ds_read_b128 v[172:175], v3 offset:1024
	ds_read_b128 v[176:179], v3 offset:2048
	ds_read_b128 v[184:187], v3 offset:3072
	s_add_u32 s48, s48, 0x80000
	s_addc_u32 s49, s49, 0
	s_mov_b32 m0, s58
	v_lshl_add_u64 v[8:9], s[48:49], 0, v[156:157]
	ds_read_b128 v[188:191], v182 offset:32768
	ds_read_b128 v[192:195], v182 offset:33792
	ds_read_b128 v[196:199], v182 offset:34816
	ds_read_b128 v[200:203], v182 offset:35840
	ds_read_b128 v[204:207], v182 offset:36864
	ds_read_b128 v[208:211], v182 offset:37888
	ds_read_b128 v[212:215], v182 offset:38912
	ds_read_b128 v[216:219], v182 offset:39936
	global_load_lds_dwordx4 v[8:9], off
	v_lshl_add_u64 v[8:9], s[48:49], 0, v[160:161]
	s_mov_b32 m0, s59
	s_nop 0
	global_load_lds_dwordx4 v[8:9], off
	s_waitcnt vmcnt(8)
	s_waitcnt lgkmcnt(0)
	s_barrier
	s_setprio 1
	s_waitcnt lgkmcnt(0)
	v_mfma_f32_16x16x32_bf16 v[130:133], v[134:137], v[188:191], v[130:133]
	v_mfma_f32_16x16x32_bf16 v[126:129], v[142:145], v[188:191], v[126:129]
	v_mfma_f32_16x16x32_bf16 v[122:125], v[134:137], v[196:199], v[122:125]
	v_mfma_f32_16x16x32_bf16 v[118:121], v[142:145], v[196:199], v[118:121]
	v_mfma_f32_16x16x32_bf16 v[114:117], v[134:137], v[204:207], v[114:117]
	v_mfma_f32_16x16x32_bf16 v[110:113], v[142:145], v[204:207], v[110:113]
	v_mfma_f32_16x16x32_bf16 v[106:109], v[134:137], v[212:215], v[106:109]
	v_mfma_f32_16x16x32_bf16 v[102:105], v[142:145], v[212:215], v[102:105]
	v_mfma_f32_16x16x32_bf16 v[130:133], v[138:141], v[192:195], v[130:133]
	v_mfma_f32_16x16x32_bf16 v[126:129], v[146:149], v[192:195], v[126:129]
	v_mfma_f32_16x16x32_bf16 v[122:125], v[138:141], v[200:203], v[122:125]
	v_mfma_f32_16x16x32_bf16 v[118:121], v[146:149], v[200:203], v[118:121]
	v_mfma_f32_16x16x32_bf16 v[114:117], v[138:141], v[208:211], v[114:117]
	v_mfma_f32_16x16x32_bf16 v[110:113], v[146:149], v[208:211], v[110:113]
	v_mfma_f32_16x16x32_bf16 v[106:109], v[138:141], v[216:219], v[106:109]
	v_mfma_f32_16x16x32_bf16 v[102:105], v[146:149], v[216:219], v[102:105]
	v_mfma_f32_16x16x32_bf16 v[98:101], v[150:153], v[188:191], v[98:101]
	v_mfma_f32_16x16x32_bf16 v[94:97], v[176:179], v[188:191], v[94:97]
	v_mfma_f32_16x16x32_bf16 v[90:93], v[150:153], v[196:199], v[90:93]
	v_mfma_f32_16x16x32_bf16 v[86:89], v[176:179], v[196:199], v[86:89]
	v_mfma_f32_16x16x32_bf16 v[82:85], v[150:153], v[204:207], v[82:85]
	v_mfma_f32_16x16x32_bf16 v[78:81], v[176:179], v[204:207], v[78:81]
	v_mfma_f32_16x16x32_bf16 v[74:77], v[150:153], v[212:215], v[74:77]
	v_mfma_f32_16x16x32_bf16 v[70:73], v[176:179], v[212:215], v[70:73]
	v_mfma_f32_16x16x32_bf16 v[98:101], v[172:175], v[192:195], v[98:101]
	v_mfma_f32_16x16x32_bf16 v[94:97], v[184:187], v[192:195], v[94:97]
	v_mfma_f32_16x16x32_bf16 v[90:93], v[172:175], v[200:203], v[90:93]
	v_mfma_f32_16x16x32_bf16 v[86:89], v[184:187], v[200:203], v[86:89]
	v_mfma_f32_16x16x32_bf16 v[82:85], v[172:175], v[208:211], v[82:85]
	v_mfma_f32_16x16x32_bf16 v[78:81], v[184:187], v[208:211], v[78:81]
	v_mfma_f32_16x16x32_bf16 v[74:77], v[172:175], v[216:219], v[74:77]
	v_mfma_f32_16x16x32_bf16 v[70:73], v[184:187], v[216:219], v[70:73]
	s_setprio 0
	s_barrier
; #define PG8_STAGE(bufoff, gbase, voff) do { _Pragma("unroll") for (int _i = 0; _i < 2; ++_i) \
;         __builtin_amdgcn_global_load_lds((const unsigned*)((const char*)(gbase) + (voff)[_i]), (PG8_LAS unsigned*)(lds + (bufoff) + ldsw + _i * 8192), 16, 0, 0); } while (0)
; #define PG8_LDA(dst, b, h) do { _Pragma("unroll") for (int m = 0; m < 4; ++m) _Pragma("unroll") for (int k = 0; k < 2; ++k) dst[m][k] = *(const PG8_LAS bf16x8*)(lds + PG8_SA(b, h) + aoff + m * 2048 + k * 1024); } while (0)
; #define PG8_MMA(ai, bj, At, Bt) do { __builtin_amdgcn_s_setprio(1); _Pragma("unroll") for (int m = 0; m < 4; ++m) _Pragma("unroll") for (int n = 0; n < 2; ++n) _Pragma("unroll") for (int k = 0; k < 2; ++k) \
;         acc[ai][bj][m][n] = __builtin_amdgcn_mfma_f32_16x16x32_bf16(Bt[n][k], At[m][k], acc[ai][bj][m][n], 0, 0, 0); __builtin_amdgcn_s_setprio(0); } while (0)
; #define PG8_WAIT_V(n) asm volatile("s_waitcnt vmcnt(" #n ")" ::: "memory")
; #define PG8_WAIT_L(n) asm volatile("s_waitcnt lgkmcnt(" #n ")" ::: "memory")
; #define PG8_BAR __builtin_amdgcn_s_barrier()
; #define PG8_SCHED __builtin_amdgcn_sched_barrier(0)
; template <class Epi, class Sched>
; __device__ __forceinline__ void gemm_phase(PG8_LAS unsigned char* lds, const Gemm g, const Sched& S, const Epi& E) {
;     ...
;             PG8_LDA(At, 1, 1); PG8_STAGE(PG8_SB(1, 0), b3, voffB); PG8_STAGE(PG8_SB(1, 1), b3 + hstepB, voffB); PG8_STAGE(PG8_SA(1, 0), a3, voffA);
;             PG8_WAIT_V(8); PG8_WAIT_L(0); PG8_BAR; PG8_MMA(1, 0, At, B0); PG8_MMA(1, 1, At, B1); PG8_BAR; PG8_SCHED;
;         }
	s_add_i32 s48, s75, s55
	v_lshl_add_u64 v[8:9], v[180:181], 0, s[14:15]
	s_mov_b32 m0, s48
	ds_read_b128 v[188:191], v182 offset:49152
	ds_read_b128 v[192:195], v182 offset:50176
	ds_read_b128 v[196:199], v182 offset:51200
	ds_read_b128 v[200:203], v182 offset:52224
	ds_read_b128 v[204:207], v182 offset:53248
	ds_read_b128 v[208:211], v182 offset:54272
	ds_read_b128 v[212:215], v182 offset:55296
	ds_read_b128 v[216:219], v182 offset:56320
	global_load_lds_dwordx4 v[8:9], off
	s_add_i32 m0, s48, 0x2000
	s_add_u32 s44, s44, 0x80080
	v_lshl_add_u64 v[8:9], v[220:221], 0, s[14:15]
	s_addc_u32 s45, s45, 0
	s_add_i32 s48, s76, s55
	global_load_lds_dwordx4 v[8:9], off
	v_lshl_add_u64 v[8:9], s[44:45], 0, v[158:159]
	s_mov_b32 m0, s48
	s_nop 0
	global_load_lds_dwordx4 v[8:9], off
	v_lshl_add_u64 v[8:9], s[44:45], 0, v[162:163]
	s_add_i32 m0, s48, 0x2000
	s_nop 0
	global_load_lds_dwordx4 v[8:9], off
	v_lshl_add_u64 v[8:9], v[222:223], 0, s[14:15]
	s_mov_b32 m0, s64
	s_nop 0
	global_load_lds_dwordx4 v[8:9], off
	v_lshl_add_u64 v[8:9], v[224:225], 0, s[14:15]
	s_mov_b32 m0, s65
	s_nop 0
	global_load_lds_dwordx4 v[8:9], off
	s_waitcnt vmcnt(8)
	s_waitcnt lgkmcnt(0)
	s_barrier
	s_setprio 1
	s_waitcnt lgkmcnt(0)
	v_mfma_f32_16x16x32_bf16 v[66:69], v[134:137], v[188:191], v[66:69]
	v_mfma_f32_16x16x32_bf16 v[62:65], v[142:145], v[188:191], v[62:65]
	v_mfma_f32_16x16x32_bf16 v[58:61], v[134:137], v[196:199], v[58:61]
	v_mfma_f32_16x16x32_bf16 v[54:57], v[142:145], v[196:199], v[54:57]
	v_mfma_f32_16x16x32_bf16 v[50:53], v[134:137], v[204:207], v[50:53]
	v_mfma_f32_16x16x32_bf16 v[46:49], v[142:145], v[204:207], v[46:49]
	v_mfma_f32_16x16x32_bf16 v[42:45], v[134:137], v[212:215], v[42:45]
	v_mfma_f32_16x16x32_bf16 v[38:41], v[142:145], v[212:215], v[38:41]
	v_mfma_f32_16x16x32_bf16 v[66:69], v[138:141], v[192:195], v[66:69]
	v_mfma_f32_16x16x32_bf16 v[62:65], v[146:149], v[192:195], v[62:65]
	v_mfma_f32_16x16x32_bf16 v[58:61], v[138:141], v[200:203], v[58:61]
	v_mfma_f32_16x16x32_bf16 v[54:57], v[146:149], v[200:203], v[54:57]
	v_mfma_f32_16x16x32_bf16 v[50:53], v[138:141], v[208:211], v[50:53]
	v_mfma_f32_16x16x32_bf16 v[46:49], v[146:149], v[208:211], v[46:49]
	v_mfma_f32_16x16x32_bf16 v[42:45], v[138:141], v[216:219], v[42:45]
	v_mfma_f32_16x16x32_bf16 v[38:41], v[146:149], v[216:219], v[38:41]
	v_mfma_f32_16x16x32_bf16 v[34:37], v[150:153], v[188:191], v[34:37]
	v_mfma_f32_16x16x32_bf16 v[30:33], v[176:179], v[188:191], v[30:33]
	v_mfma_f32_16x16x32_bf16 v[26:29], v[150:153], v[196:199], v[26:29]
	v_mfma_f32_16x16x32_bf16 v[22:25], v[176:179], v[196:199], v[22:25]
	v_mfma_f32_16x16x32_bf16 v[18:21], v[150:153], v[204:207], v[18:21]
	v_mfma_f32_16x16x32_bf16 v[14:17], v[176:179], v[204:207], v[14:17]
	v_mfma_f32_16x16x32_bf16 v[8:11], v[150:153], v[212:215], v[10:13]
	v_mfma_f32_16x16x32_bf16 v[4:7], v[176:179], v[212:215], v[4:7]
	v_mfma_f32_16x16x32_bf16 v[34:37], v[172:175], v[192:195], v[34:37]
	v_mfma_f32_16x16x32_bf16 v[30:33], v[184:187], v[192:195], v[30:33]
	v_mfma_f32_16x16x32_bf16 v[26:29], v[172:175], v[200:203], v[26:29]
	v_mfma_f32_16x16x32_bf16 v[22:25], v[184:187], v[200:203], v[22:25]
	v_mfma_f32_16x16x32_bf16 v[18:21], v[172:175], v[208:211], v[18:21]
	v_mfma_f32_16x16x32_bf16 v[14:17], v[184:187], v[208:211], v[14:17]
	v_mfma_f32_16x16x32_bf16 v[10:13], v[172:175], v[216:219], v[8:11]
	v_mfma_f32_16x16x32_bf16 v[6:9], v[184:187], v[216:219], v[4:7]
	s_setprio 0
	s_barrier
	s_add_i32 s74, s74, 2
	s_add_u32 s46, s46, 0x100
	s_addc_u32 s47, s47, 0
	s_add_u32 s72, s72, 0x100
	s_addc_u32 s73, s73, 0
	s_cmp_gt_u32 s74, 29
	s_cbranch_scc0 .LBB0_611
	s_and_b64 vcc, exec, s[16:17]
	s_cbranch_vccz .LBB0_614
	s_barrier

; #define PG8_STAGE(bufoff, gbase, voff) do { _Pragma("unroll") for (int _i = 0; _i < 2; ++_i) \
;         __builtin_amdgcn_global_load_lds((const unsigned*)((const char*)(gbase) + (voff)[_i]), (PG8_LAS unsigned*)(lds + (bufoff) + ldsw + _i * 8192), 16, 0, 0); } while (0)
; #define PG8_LDA(dst, b, h) do { _Pragma("unroll") for (int m = 0; m < 4; ++m) _Pragma("unroll") for (int k = 0; k < 2; ++k) dst[m][k] = *(const PG8_LAS bf16x8*)(lds + PG8_SA(b, h) + aoff + m * 2048 + k * 1024); } while (0)
; #define PG8_LDB(dst, b, h) do { _Pragma("unroll") for (int n = 0; n < 2; ++n) _Pragma("unroll") for (int k = 0; k < 2; ++k) dst[n][k] = *(const PG8_LAS bf16x8*)(lds + PG8_SB(b, h) + boff + n * 2048 + k * 1024); } while (0)
; #define PG8_MMA(ai, bj, At, Bt) do { __builtin_amdgcn_s_setprio(1); _Pragma("unroll") for (int m = 0; m < 4; ++m) _Pragma("unroll") for (int n = 0; n < 2; ++n) _Pragma("unroll") for (int k = 0; k < 2; ++k) \
;         acc[ai][bj][m][n] = __builtin_amdgcn_mfma_f32_16x16x32_bf16(Bt[n][k], At[m][k], acc[ai][bj][m][n], 0, 0, 0); __builtin_amdgcn_s_setprio(0); } while (0)
; #define PG8_WAIT_V(n) asm volatile("s_waitcnt vmcnt(" #n ")" ::: "memory")
; #define PG8_WAIT_L(n) asm volatile("s_waitcnt lgkmcnt(" #n ")" ::: "memory")
; #define PG8_BAR __builtin_amdgcn_s_barrier()
; #define PG8_SCHED __builtin_amdgcn_sched_barrier(0)
; template <class Epi, class Sched>
; __device__ __forceinline__ void gemm_phase(PG8_LAS unsigned char* lds, const Gemm g, const Sched& S, const Epi& E) {
;     ...
;             PG8_LDB(B0, 0, 0); PG8_LDB(B1, 0, 1); PG8_SCHED; PG8_LDA(At, 0, 0); PG8_STAGE(PG8_SA(1, 1), a1 + hstepA, voffA);
;             PG8_WAIT_V(8); PG8_WAIT_L(0); PG8_BAR; PG8_MMA(0, 0, At, B0); PG8_MMA(0, 1, At, B1); PG8_BAR; PG8_SCHED;
;             PG8_LDA(At, 0, 1); PG8_STAGE(PG8_SB(0, 0), b2, voffB); PG8_STAGE(PG8_SB(0, 1), b2 + hstepB, voffB); PG8_STAGE(PG8_SA(0, 0), a2, voffA);
;             PG8_WAIT_V(8); PG8_WAIT_L(0); PG8_BAR; PG8_MMA(1, 0, At, B0); PG8_MMA(1, 1, At, B1); PG8_BAR; PG8_SCHED;
.LBB0_701:
	ds_read_b128 v[74:77], v178
	ds_read_b128 v[78:81], v178 offset:1024
	ds_read_b128 v[90:93], v178 offset:2048
	ds_read_b128 v[94:97], v178 offset:3072
	ds_read_b128 v[162:165], v179
	ds_read_b128 v[166:169], v179 offset:1024
	ds_read_b128 v[170:173], v179 offset:2048
	ds_read_b128 v[182:185], v179 offset:3072
	s_add_u32 s28, s26, 0xfff80080
	s_addc_u32 s29, s27, -1
	s_cmp_eq_u32 s52, 28
	s_cselect_b32 s31, s3, s29
	s_cselect_b32 s30, s17, s28
	s_cselect_b32 s29, s15, s51
	s_cselect_b32 s28, s33, s50
	v_lshl_add_u64 v[174:175], s[26:27], 0, v[156:157]
	s_add_i32 m0, s25, 0xc000
	ds_read_b128 v[186:189], v180
	ds_read_b128 v[190:193], v180 offset:1024
	ds_read_b128 v[194:197], v180 offset:2048
	ds_read_b128 v[198:201], v180 offset:3072
	ds_read_b128 v[202:205], v180 offset:4096
	ds_read_b128 v[206:209], v180 offset:5120
	ds_read_b128 v[210:213], v180 offset:6144
	ds_read_b128 v[214:217], v180 offset:7168
	global_load_lds_dwordx4 v[174:175], off
	v_lshl_add_u64 v[174:175], s[26:27], 0, v[158:159]
	s_add_i32 m0, s25, 0xe000
	s_nop 0
	global_load_lds_dwordx4 v[174:175], off
	s_waitcnt vmcnt(8)
	s_waitcnt lgkmcnt(0)
	s_barrier
	s_setprio 1
	s_waitcnt lgkmcnt(0)
	v_mfma_f32_16x16x32_bf16 v[142:145], v[74:77], v[186:189], v[142:145]
	v_mfma_f32_16x16x32_bf16 v[138:141], v[90:93], v[186:189], v[138:141]
	v_mfma_f32_16x16x32_bf16 v[126:129], v[74:77], v[194:197], v[126:129]
	v_mfma_f32_16x16x32_bf16 v[122:125], v[90:93], v[194:197], v[122:125]
	v_mfma_f32_16x16x32_bf16 v[110:113], v[74:77], v[202:205], v[110:113]
	v_mfma_f32_16x16x32_bf16 v[106:109], v[90:93], v[202:205], v[106:109]
	v_mfma_f32_16x16x32_bf16 v[86:89], v[74:77], v[210:213], v[86:89]
	v_mfma_f32_16x16x32_bf16 v[82:85], v[90:93], v[210:213], v[82:85]
	v_mfma_f32_16x16x32_bf16 v[142:145], v[78:81], v[190:193], v[142:145]
	v_mfma_f32_16x16x32_bf16 v[138:141], v[94:97], v[190:193], v[138:141]
	v_mfma_f32_16x16x32_bf16 v[126:129], v[78:81], v[198:201], v[126:129]
	v_mfma_f32_16x16x32_bf16 v[122:125], v[94:97], v[198:201], v[122:125]
	v_mfma_f32_16x16x32_bf16 v[110:113], v[78:81], v[206:209], v[110:113]
	v_mfma_f32_16x16x32_bf16 v[106:109], v[94:97], v[206:209], v[106:109]
	v_mfma_f32_16x16x32_bf16 v[86:89], v[78:81], v[214:217], v[86:89]
	v_mfma_f32_16x16x32_bf16 v[82:85], v[94:97], v[214:217], v[82:85]
	v_mfma_f32_16x16x32_bf16 v[134:137], v[162:165], v[186:189], v[134:137]
	v_mfma_f32_16x16x32_bf16 v[130:133], v[170:173], v[186:189], v[130:133]
	v_mfma_f32_16x16x32_bf16 v[118:121], v[162:165], v[194:197], v[118:121]
	v_mfma_f32_16x16x32_bf16 v[114:117], v[170:173], v[194:197], v[114:117]
	v_mfma_f32_16x16x32_bf16 v[102:105], v[162:165], v[202:205], v[102:105]
	v_mfma_f32_16x16x32_bf16 v[98:101], v[170:173], v[202:205], v[98:101]
	v_mfma_f32_16x16x32_bf16 v[70:73], v[162:165], v[210:213], v[70:73]
	v_mfma_f32_16x16x32_bf16 v[66:69], v[170:173], v[210:213], v[66:69]
	v_mfma_f32_16x16x32_bf16 v[134:137], v[166:169], v[190:193], v[134:137]
	v_mfma_f32_16x16x32_bf16 v[130:133], v[182:185], v[190:193], v[130:133]
	v_mfma_f32_16x16x32_bf16 v[118:121], v[166:169], v[198:201], v[118:121]
	v_mfma_f32_16x16x32_bf16 v[114:117], v[182:185], v[198:201], v[114:117]
	v_mfma_f32_16x16x32_bf16 v[102:105], v[166:169], v[206:209], v[102:105]
	v_mfma_f32_16x16x32_bf16 v[98:101], v[182:185], v[206:209], v[98:101]
	v_mfma_f32_16x16x32_bf16 v[70:73], v[166:169], v[214:217], v[70:73]
	v_mfma_f32_16x16x32_bf16 v[66:69], v[182:185], v[214:217], v[66:69]
	s_setprio 0
	s_barrier
	s_add_i32 s53, s48, s38
	v_lshl_add_u64 v[174:175], s[28:29], 0, v[148:149]
	s_mov_b32 m0, s53
	ds_read_b128 v[186:189], v180 offset:16384
	ds_read_b128 v[190:193], v180 offset:17408
	ds_read_b128 v[194:197], v180 offset:18432
	ds_read_b128 v[198:201], v180 offset:19456
	ds_read_b128 v[202:205], v180 offset:20480
	ds_read_b128 v[206:209], v180 offset:21504
	ds_read_b128 v[210:213], v180 offset:22528
	ds_read_b128 v[214:217], v180 offset:23552
	global_load_lds_dwordx4 v[174:175], off
	s_add_i32 m0, s53, 0x2000
	s_add_u32 s54, s28, 0x80000
	v_lshl_add_u64 v[218:219], s[28:29], 0, v[152:153]
	s_addc_u32 s55, s29, 0
	s_add_i32 s53, s49, s38
	global_load_lds_dwordx4 v[218:219], off
	v_lshl_add_u64 v[220:221], s[54:55], 0, v[148:149]
	s_mov_b32 m0, s53
	v_lshl_add_u64 v[222:223], s[30:31], 0, v[150:151]
	global_load_lds_dwordx4 v[220:221], off
	v_lshl_add_u64 v[220:221], s[54:55], 0, v[152:153]
	s_add_i32 m0, s53, 0x2000
	s_nop 0
	global_load_lds_dwordx4 v[220:221], off
	v_lshl_add_u64 v[220:221], s[30:31], 0, v[146:147]
	s_mov_b32 m0, s25
	s_nop 0
	global_load_lds_dwordx4 v[220:221], off
	s_mov_b32 m0, s39
	s_nop 0
	global_load_lds_dwordx4 v[222:223], off
	s_waitcnt vmcnt(8)
	s_waitcnt lgkmcnt(0)
	s_barrier
; #define PG8_STAGE(bufoff, gbase, voff) do { _Pragma("unroll") for (int _i = 0; _i < 2; ++_i) \
;         __builtin_amdgcn_global_load_lds((const unsigned*)((const char*)(gbase) + (voff)[_i]), (PG8_LAS unsigned*)(lds + (bufoff) + ldsw + _i * 8192), 16, 0, 0); } while (0)
; #define PG8_LDA(dst, b, h) do { _Pragma("unroll") for (int m = 0; m < 4; ++m) _Pragma("unroll") for (int k = 0; k < 2; ++k) dst[m][k] = *(const PG8_LAS bf16x8*)(lds + PG8_SA(b, h) + aoff + m * 2048 + k * 1024); } while (0)
; #define PG8_LDB(dst, b, h) do { _Pragma("unroll") for (int n = 0; n < 2; ++n) _Pragma("unroll") for (int k = 0; k < 2; ++k) dst[n][k] = *(const PG8_LAS bf16x8*)(lds + PG8_SB(b, h) + boff + n * 2048 + k * 1024); } while (0)
; #define PG8_MMA(ai, bj, At, Bt) do { __builtin_amdgcn_s_setprio(1); _Pragma("unroll") for (int m = 0; m < 4; ++m) _Pragma("unroll") for (int n = 0; n < 2; ++n) _Pragma("unroll") for (int k = 0; k < 2; ++k) \
;         acc[ai][bj][m][n] = __builtin_amdgcn_mfma_f32_16x16x32_bf16(Bt[n][k], At[m][k], acc[ai][bj][m][n], 0, 0, 0); __builtin_amdgcn_s_setprio(0); } while (0)
; #define PG8_WAIT_V(n) asm volatile("s_waitcnt vmcnt(" #n ")" ::: "memory")
; #define PG8_WAIT_L(n) asm volatile("s_waitcnt lgkmcnt(" #n ")" ::: "memory")
; #define PG8_BAR __builtin_amdgcn_s_barrier()
; #define PG8_SCHED __builtin_amdgcn_sched_barrier(0)
; template <class Epi, class Sched>
; __device__ __forceinline__ void gemm_phase(PG8_LAS unsigned char* lds, const Gemm g, const Sched& S, const Epi& E) {
;     ...
;             PG8_WAIT_V(8); PG8_WAIT_L(0); PG8_BAR; PG8_MMA(1, 0, At, B0); PG8_MMA(1, 1, At, B1); PG8_BAR; PG8_SCHED;
;             PG8_LDB(B0, 1, 0); PG8_LDB(B1, 1, 1); PG8_SCHED; PG8_LDA(At, 1, 0); PG8_STAGE(PG8_SA(0, 1), a2 + hstepA, voffA);
;             PG8_WAIT_V(8); PG8_WAIT_L(0); PG8_BAR; PG8_MMA(0, 0, At, B0); PG8_MMA(0, 1, At, B1); PG8_BAR; PG8_SCHED;
;             PG8_LDA(At, 1, 1); PG8_STAGE(PG8_SB(1, 0), b3, voffB); PG8_STAGE(PG8_SB(1, 1), b3 + hstepB, voffB); PG8_STAGE(PG8_SA(1, 0), a3, voffA);
	s_setprio 1
	s_waitcnt lgkmcnt(0)
	v_mfma_f32_16x16x32_bf16 v[62:65], v[74:77], v[186:189], v[62:65]
	v_mfma_f32_16x16x32_bf16 v[58:61], v[90:93], v[186:189], v[58:61]
	v_mfma_f32_16x16x32_bf16 v[46:49], v[74:77], v[194:197], v[46:49]
	v_mfma_f32_16x16x32_bf16 v[42:45], v[90:93], v[194:197], v[42:45]
	v_mfma_f32_16x16x32_bf16 v[30:33], v[74:77], v[202:205], v[30:33]
	v_mfma_f32_16x16x32_bf16 v[26:29], v[90:93], v[202:205], v[26:29]
	v_mfma_f32_16x16x32_bf16 v[14:17], v[74:77], v[210:213], v[14:17]
	v_mfma_f32_16x16x32_bf16 v[10:13], v[90:93], v[210:213], v[10:13]
	v_mfma_f32_16x16x32_bf16 v[62:65], v[78:81], v[190:193], v[62:65]
	v_mfma_f32_16x16x32_bf16 v[58:61], v[94:97], v[190:193], v[58:61]
	v_mfma_f32_16x16x32_bf16 v[46:49], v[78:81], v[198:201], v[46:49]
	v_mfma_f32_16x16x32_bf16 v[42:45], v[94:97], v[198:201], v[42:45]
	v_mfma_f32_16x16x32_bf16 v[30:33], v[78:81], v[206:209], v[30:33]
	v_mfma_f32_16x16x32_bf16 v[26:29], v[94:97], v[206:209], v[26:29]
	v_mfma_f32_16x16x32_bf16 v[14:17], v[78:81], v[214:217], v[14:17]
	v_mfma_f32_16x16x32_bf16 v[10:13], v[94:97], v[214:217], v[10:13]
	v_mfma_f32_16x16x32_bf16 v[54:57], v[162:165], v[186:189], v[54:57]
	v_mfma_f32_16x16x32_bf16 v[50:53], v[170:173], v[186:189], v[50:53]
	v_mfma_f32_16x16x32_bf16 v[38:41], v[162:165], v[194:197], v[38:41]
	v_mfma_f32_16x16x32_bf16 v[34:37], v[170:173], v[194:197], v[34:37]
	v_mfma_f32_16x16x32_bf16 v[22:25], v[162:165], v[202:205], v[22:25]
	v_mfma_f32_16x16x32_bf16 v[18:21], v[170:173], v[202:205], v[18:21]
	v_mfma_f32_16x16x32_bf16 v[6:9], v[162:165], v[210:213], v[6:9]
	v_mfma_f32_16x16x32_bf16 v[2:5], v[170:173], v[210:213], v[2:5]
	v_mfma_f32_16x16x32_bf16 v[54:57], v[166:169], v[190:193], v[54:57]
	v_mfma_f32_16x16x32_bf16 v[50:53], v[182:185], v[190:193], v[50:53]
	v_mfma_f32_16x16x32_bf16 v[38:41], v[166:169], v[198:201], v[38:41]
	v_mfma_f32_16x16x32_bf16 v[34:37], v[182:185], v[198:201], v[34:37]
	v_mfma_f32_16x16x32_bf16 v[22:25], v[166:169], v[206:209], v[22:25]
	v_mfma_f32_16x16x32_bf16 v[18:21], v[182:185], v[206:209], v[18:21]
	v_mfma_f32_16x16x32_bf16 v[6:9], v[166:169], v[214:217], v[6:9]
	v_mfma_f32_16x16x32_bf16 v[2:5], v[182:185], v[214:217], v[2:5]
	s_setprio 0
	s_barrier
	s_add_i32 s53, 0, 0x18000
	s_add_i32 s54, 0, 0x1c000
	v_add_u32_e32 v94, s53, v176
	v_add_u32_e32 v182, s54, v176
	ds_read_b128 v[74:77], v94
	ds_read_b128 v[78:81], v94 offset:1024
	ds_read_b128 v[90:93], v94 offset:2048
	ds_read_b128 v[94:97], v94 offset:3072
	ds_read_b128 v[162:165], v182
	ds_read_b128 v[166:169], v182 offset:1024
	ds_read_b128 v[170:173], v182 offset:2048
	ds_read_b128 v[182:185], v182 offset:3072
	s_add_u32 s30, s30, 0x80000
	s_addc_u32 s31, s31, 0
	s_mov_b32 m0, s40
	v_lshl_add_u64 v[224:225], s[30:31], 0, v[146:147]
	ds_read_b128 v[186:189], v180 offset:32768
	ds_read_b128 v[190:193], v180 offset:33792
	ds_read_b128 v[194:197], v180 offset:34816
	ds_read_b128 v[198:201], v180 offset:35840
	ds_read_b128 v[202:205], v180 offset:36864
	ds_read_b128 v[206:209], v180 offset:37888
	ds_read_b128 v[210:213], v180 offset:38912
	ds_read_b128 v[214:217], v180 offset:39936
	global_load_lds_dwordx4 v[224:225], off
	v_lshl_add_u64 v[224:225], s[30:31], 0, v[150:151]
	s_mov_b32 m0, s41
	s_nop 0
	global_load_lds_dwordx4 v[224:225], off
	s_waitcnt vmcnt(8)
	s_waitcnt lgkmcnt(0)
	s_barrier
	s_setprio 1
	s_waitcnt lgkmcnt(0)
	v_mfma_f32_16x16x32_bf16 v[142:145], v[74:77], v[186:189], v[142:145]
	v_mfma_f32_16x16x32_bf16 v[138:141], v[90:93], v[186:189], v[138:141]
	v_mfma_f32_16x16x32_bf16 v[126:129], v[74:77], v[194:197], v[126:129]
	v_mfma_f32_16x16x32_bf16 v[122:125], v[90:93], v[194:197], v[122:125]
	v_mfma_f32_16x16x32_bf16 v[110:113], v[74:77], v[202:205], v[110:113]
	v_mfma_f32_16x16x32_bf16 v[106:109], v[90:93], v[202:205], v[106:109]
	v_mfma_f32_16x16x32_bf16 v[86:89], v[74:77], v[210:213], v[86:89]
	v_mfma_f32_16x16x32_bf16 v[82:85], v[90:93], v[210:213], v[82:85]
	v_mfma_f32_16x16x32_bf16 v[142:145], v[78:81], v[190:193], v[142:145]
	v_mfma_f32_16x16x32_bf16 v[138:141], v[94:97], v[190:193], v[138:141]
	v_mfma_f32_16x16x32_bf16 v[126:129], v[78:81], v[198:201], v[126:129]
	v_mfma_f32_16x16x32_bf16 v[122:125], v[94:97], v[198:201], v[122:125]
	v_mfma_f32_16x16x32_bf16 v[110:113], v[78:81], v[206:209], v[110:113]
	v_mfma_f32_16x16x32_bf16 v[106:109], v[94:97], v[206:209], v[106:109]
	v_mfma_f32_16x16x32_bf16 v[86:89], v[78:81], v[214:217], v[86:89]
	v_mfma_f32_16x16x32_bf16 v[82:85], v[94:97], v[214:217], v[82:85]
	v_mfma_f32_16x16x32_bf16 v[134:137], v[162:165], v[186:189], v[134:137]
	v_mfma_f32_16x16x32_bf16 v[130:133], v[170:173], v[186:189], v[130:133]
	v_mfma_f32_16x16x32_bf16 v[118:121], v[162:165], v[194:197], v[118:121]
	v_mfma_f32_16x16x32_bf16 v[114:117], v[170:173], v[194:197], v[114:117]
	v_mfma_f32_16x16x32_bf16 v[102:105], v[162:165], v[202:205], v[102:105]
	v_mfma_f32_16x16x32_bf16 v[98:101], v[170:173], v[202:205], v[98:101]
	v_mfma_f32_16x16x32_bf16 v[70:73], v[162:165], v[210:213], v[70:73]
	v_mfma_f32_16x16x32_bf16 v[66:69], v[170:173], v[210:213], v[66:69]
	v_mfma_f32_16x16x32_bf16 v[134:137], v[166:169], v[190:193], v[134:137]
	v_mfma_f32_16x16x32_bf16 v[130:133], v[182:185], v[190:193], v[130:133]
	v_mfma_f32_16x16x32_bf16 v[118:121], v[166:169], v[198:201], v[118:121]
	v_mfma_f32_16x16x32_bf16 v[114:117], v[182:185], v[198:201], v[114:117]
	v_mfma_f32_16x16x32_bf16 v[102:105], v[166:169], v[206:209], v[102:105]
	v_mfma_f32_16x16x32_bf16 v[98:101], v[182:185], v[206:209], v[98:101]
	v_mfma_f32_16x16x32_bf16 v[70:73], v[166:169], v[214:217], v[70:73]
	v_mfma_f32_16x16x32_bf16 v[66:69], v[182:185], v[214:217], v[66:69]
	s_setprio 0
	s_barrier
; #define PG8_STAGE(bufoff, gbase, voff) do { _Pragma("unroll") for (int _i = 0; _i < 2; ++_i) \
;         __builtin_amdgcn_global_load_lds((const unsigned*)((const char*)(gbase) + (voff)[_i]), (PG8_LAS unsigned*)(lds + (bufoff) + ldsw + _i * 8192), 16, 0, 0); } while (0)
; #define PG8_LDA(dst, b, h) do { _Pragma("unroll") for (int m = 0; m < 4; ++m) _Pragma("unroll") for (int k = 0; k < 2; ++k) dst[m][k] = *(const PG8_LAS bf16x8*)(lds + PG8_SA(b, h) + aoff + m * 2048 + k * 1024); } while (0)
; #define PG8_MMA(ai, bj, At, Bt) do { __builtin_amdgcn_s_setprio(1); _Pragma("unroll") for (int m = 0; m < 4; ++m) _Pragma("unroll") for (int n = 0; n < 2; ++n) _Pragma("unroll") for (int k = 0; k < 2; ++k) \
;         acc[ai][bj][m][n] = __builtin_amdgcn_mfma_f32_16x16x32_bf16(Bt[n][k], At[m][k], acc[ai][bj][m][n], 0, 0, 0); __builtin_amdgcn_s_setprio(0); } while (0)
; #define PG8_WAIT_V(n) asm volatile("s_waitcnt vmcnt(" #n ")" ::: "memory")
; #define PG8_WAIT_L(n) asm volatile("s_waitcnt lgkmcnt(" #n ")" ::: "memory")
; #define PG8_BAR __builtin_amdgcn_s_barrier()
; #define PG8_SCHED __builtin_amdgcn_sched_barrier(0)
; template <class Epi, class Sched>
; __device__ __forceinline__ void gemm_phase(PG8_LAS unsigned char* lds, const Gemm g, const Sched& S, const Epi& E) {
;     ...
;             PG8_LDA(At, 1, 1); PG8_STAGE(PG8_SB(1, 0), b3, voffB); PG8_STAGE(PG8_SB(1, 1), b3 + hstepB, voffB); PG8_STAGE(PG8_SA(1, 0), a3, voffA);
;             PG8_WAIT_V(8); PG8_WAIT_L(0); PG8_BAR; PG8_MMA(1, 0, At, B0); PG8_MMA(1, 1, At, B1); PG8_BAR; PG8_SCHED;
;         }
	s_add_i32 s30, s53, s38
	v_lshl_add_u64 v[174:175], v[174:175], 0, s[10:11]
	s_mov_b32 m0, s30
	ds_read_b128 v[186:189], v180 offset:49152
	ds_read_b128 v[190:193], v180 offset:50176
	ds_read_b128 v[194:197], v180 offset:51200
	ds_read_b128 v[198:201], v180 offset:52224
	ds_read_b128 v[202:205], v180 offset:53248
	ds_read_b128 v[206:209], v180 offset:54272
	ds_read_b128 v[210:213], v180 offset:55296
	ds_read_b128 v[214:217], v180 offset:56320
	global_load_lds_dwordx4 v[174:175], off
	s_add_i32 m0, s30, 0x2000
	s_add_u32 s28, s28, 0x80080
	v_lshl_add_u64 v[174:175], v[218:219], 0, s[10:11]
	s_addc_u32 s29, s29, 0
	s_add_i32 s30, s54, s38
	global_load_lds_dwordx4 v[174:175], off
	v_lshl_add_u64 v[174:175], s[28:29], 0, v[148:149]
	s_mov_b32 m0, s30
	s_nop 0
	global_load_lds_dwordx4 v[174:175], off
	v_lshl_add_u64 v[174:175], s[28:29], 0, v[152:153]
	s_add_i32 m0, s30, 0x2000
	s_nop 0
	global_load_lds_dwordx4 v[174:175], off
	v_lshl_add_u64 v[174:175], v[220:221], 0, s[10:11]
	s_mov_b32 m0, s44
	s_nop 0
	global_load_lds_dwordx4 v[174:175], off
	v_lshl_add_u64 v[174:175], v[222:223], 0, s[10:11]
	s_mov_b32 m0, s45
	s_nop 0
	global_load_lds_dwordx4 v[174:175], off
	s_waitcnt vmcnt(8)
	s_waitcnt lgkmcnt(0)
	s_barrier
	s_setprio 1
	s_waitcnt lgkmcnt(0)
	v_mfma_f32_16x16x32_bf16 v[62:65], v[74:77], v[186:189], v[62:65]
	v_mfma_f32_16x16x32_bf16 v[58:61], v[90:93], v[186:189], v[58:61]
	v_mfma_f32_16x16x32_bf16 v[46:49], v[74:77], v[194:197], v[46:49]
	v_mfma_f32_16x16x32_bf16 v[42:45], v[90:93], v[194:197], v[42:45]
	v_mfma_f32_16x16x32_bf16 v[30:33], v[74:77], v[202:205], v[30:33]
	v_mfma_f32_16x16x32_bf16 v[26:29], v[90:93], v[202:205], v[26:29]
	v_mfma_f32_16x16x32_bf16 v[14:17], v[74:77], v[210:213], v[14:17]
	v_mfma_f32_16x16x32_bf16 v[10:13], v[90:93], v[210:213], v[10:13]
	v_mfma_f32_16x16x32_bf16 v[62:65], v[78:81], v[190:193], v[62:65]
	v_mfma_f32_16x16x32_bf16 v[58:61], v[94:97], v[190:193], v[58:61]
	v_mfma_f32_16x16x32_bf16 v[46:49], v[78:81], v[198:201], v[46:49]
	v_mfma_f32_16x16x32_bf16 v[42:45], v[94:97], v[198:201], v[42:45]
	v_mfma_f32_16x16x32_bf16 v[30:33], v[78:81], v[206:209], v[30:33]
	v_mfma_f32_16x16x32_bf16 v[26:29], v[94:97], v[206:209], v[26:29]
	v_mfma_f32_16x16x32_bf16 v[14:17], v[78:81], v[214:217], v[14:17]
	v_mfma_f32_16x16x32_bf16 v[10:13], v[94:97], v[214:217], v[10:13]
	v_mfma_f32_16x16x32_bf16 v[54:57], v[162:165], v[186:189], v[54:57]
	v_mfma_f32_16x16x32_bf16 v[50:53], v[170:173], v[186:189], v[50:53]
	v_mfma_f32_16x16x32_bf16 v[38:41], v[162:165], v[194:197], v[38:41]
	v_mfma_f32_16x16x32_bf16 v[34:37], v[170:173], v[194:197], v[34:37]
	v_mfma_f32_16x16x32_bf16 v[22:25], v[162:165], v[202:205], v[22:25]
	v_mfma_f32_16x16x32_bf16 v[18:21], v[170:173], v[202:205], v[18:21]
	v_mfma_f32_16x16x32_bf16 v[6:9], v[162:165], v[210:213], v[6:9]
	v_mfma_f32_16x16x32_bf16 v[2:5], v[170:173], v[210:213], v[2:5]
	v_mfma_f32_16x16x32_bf16 v[54:57], v[166:169], v[190:193], v[54:57]
	v_mfma_f32_16x16x32_bf16 v[50:53], v[182:185], v[190:193], v[50:53]
	v_mfma_f32_16x16x32_bf16 v[38:41], v[166:169], v[198:201], v[38:41]
	v_mfma_f32_16x16x32_bf16 v[34:37], v[182:185], v[198:201], v[34:37]
	v_mfma_f32_16x16x32_bf16 v[22:25], v[166:169], v[206:209], v[22:25]
	v_mfma_f32_16x16x32_bf16 v[18:21], v[182:185], v[206:209], v[18:21]
	v_mfma_f32_16x16x32_bf16 v[6:9], v[166:169], v[214:217], v[6:9]
	v_mfma_f32_16x16x32_bf16 v[2:5], v[182:185], v[214:217], v[2:5]
	s_setprio 0
	s_barrier
	s_add_i32 s52, s52, 2
	s_add_u32 s26, s26, 0x100
	s_addc_u32 s27, s27, 0
	s_add_u32 s50, s50, 0x100
	s_addc_u32 s51, s51, 0
	s_cmp_gt_u32 s52, 29
	s_cbranch_scc0 .LBB0_701
	s_and_b64 vcc, exec, s[12:13]
	s_cbranch_vccz .LBB0_704
	s_barrier

; #define PG8_STAGE(bufoff, gbase, voff) do { _Pragma("unroll") for (int _i = 0; _i < 2; ++_i) \
;         __builtin_amdgcn_global_load_lds((const unsigned*)((const char*)(gbase) + (voff)[_i]), (PG8_LAS unsigned*)(lds + (bufoff) + ldsw + _i * 8192), 16, 0, 0); } while (0)
; #define PG8_LDA(dst, b, h) do { _Pragma("unroll") for (int m = 0; m < 4; ++m) _Pragma("unroll") for (int k = 0; k < 2; ++k) dst[m][k] = *(const PG8_LAS bf16x8*)(lds + PG8_SA(b, h) + aoff + m * 2048 + k * 1024); } while (0)
; #define PG8_LDB(dst, b, h) do { _Pragma("unroll") for (int n = 0; n < 2; ++n) _Pragma("unroll") for (int k = 0; k < 2; ++k) dst[n][k] = *(const PG8_LAS bf16x8*)(lds + PG8_SB(b, h) + boff + n * 2048 + k * 1024); } while (0)
; #define PG8_MMA(ai, bj, At, Bt) do { __builtin_amdgcn_s_setprio(1); _Pragma("unroll") for (int m = 0; m < 4; ++m) _Pragma("unroll") for (int n = 0; n < 2; ++n) _Pragma("unroll") for (int k = 0; k < 2; ++k) \
;         acc[ai][bj][m][n] = __builtin_amdgcn_mfma_f32_16x16x32_bf16(Bt[n][k], At[m][k], acc[ai][bj][m][n], 0, 0, 0); __builtin_amdgcn_s_setprio(0); } while (0)
; #define PG8_WAIT_V(n) asm volatile("s_waitcnt vmcnt(" #n ")" ::: "memory")
; #define PG8_WAIT_L(n) asm volatile("s_waitcnt lgkmcnt(" #n ")" ::: "memory")
; #define PG8_BAR __builtin_amdgcn_s_barrier()
; #define PG8_SCHED __builtin_amdgcn_sched_barrier(0)
; template <class Epi, class Sched>
; __device__ __forceinline__ void gemm_phase(PG8_LAS unsigned char* lds, const Gemm g, const Sched& S, const Epi& E) {
;     ...
;             PG8_LDB(B0, 0, 0); PG8_LDB(B1, 0, 1); PG8_SCHED; PG8_LDA(At, 0, 0); PG8_STAGE(PG8_SA(1, 1), a1 + hstepA, voffA);
;             PG8_WAIT_V(8); PG8_WAIT_L(0); PG8_BAR; PG8_MMA(0, 0, At, B0); PG8_MMA(0, 1, At, B1); PG8_BAR; PG8_SCHED;
;             PG8_LDA(At, 0, 1); PG8_STAGE(PG8_SB(0, 0), b2, voffB); PG8_STAGE(PG8_SB(0, 1), b2 + hstepB, voffB); PG8_STAGE(PG8_SA(0, 0), a2, voffA);
;             PG8_WAIT_V(8); PG8_WAIT_L(0); PG8_BAR; PG8_MMA(1, 0, At, B0); PG8_MMA(1, 1, At, B1); PG8_BAR; PG8_SCHED;
.LBB0_791:
	ds_read_b128 v[130:133], v172
	ds_read_b128 v[134:137], v172 offset:1024
	ds_read_b128 v[138:141], v172 offset:2048
	ds_read_b128 v[142:145], v172 offset:3072
	ds_read_b128 v[166:169], v173
	ds_read_b128 v[176:179], v173 offset:1024
	ds_read_b128 v[180:183], v173 offset:2048
	ds_read_b128 v[184:187], v173 offset:3072
	s_add_u32 s26, s24, 0xfff80080
	s_addc_u32 s27, s25, -1
	s_cmp_eq_u32 s60, 28
	s_cselect_b32 s29, s6, s27
	s_cselect_b32 s28, s17, s26
	s_cselect_b32 s27, s15, s59
	s_cselect_b32 s26, s57, s58
	v_lshl_add_u64 v[170:171], s[24:25], 0, v[160:161]
	s_add_i32 m0, s39, 0xc000
	ds_read_b128 v[188:191], v174
	ds_read_b128 v[192:195], v174 offset:1024
	ds_read_b128 v[196:199], v174 offset:2048
	ds_read_b128 v[200:203], v174 offset:3072
	ds_read_b128 v[204:207], v174 offset:4096
	ds_read_b128 v[208:211], v174 offset:5120
	ds_read_b128 v[212:215], v174 offset:6144
	ds_read_b128 v[216:219], v174 offset:7168
	global_load_lds_dwordx4 v[170:171], off
	v_lshl_add_u64 v[170:171], s[24:25], 0, v[162:163]
	s_add_i32 m0, s39, 0xe000
	s_nop 0
	global_load_lds_dwordx4 v[170:171], off
	s_waitcnt vmcnt(8)
	s_waitcnt lgkmcnt(0)
	s_barrier
	s_setprio 1
	s_waitcnt lgkmcnt(0)
	v_mfma_f32_16x16x32_bf16 v[126:129], v[130:133], v[188:191], v[126:129]
	v_mfma_f32_16x16x32_bf16 v[122:125], v[138:141], v[188:191], v[122:125]
	v_mfma_f32_16x16x32_bf16 v[110:113], v[130:133], v[196:199], v[110:113]
	v_mfma_f32_16x16x32_bf16 v[106:109], v[138:141], v[196:199], v[106:109]
	v_mfma_f32_16x16x32_bf16 v[94:97], v[130:133], v[204:207], v[94:97]
	v_mfma_f32_16x16x32_bf16 v[90:93], v[138:141], v[204:207], v[90:93]
	v_mfma_f32_16x16x32_bf16 v[78:81], v[130:133], v[212:215], v[78:81]
	v_mfma_f32_16x16x32_bf16 v[74:77], v[138:141], v[212:215], v[74:77]
	v_mfma_f32_16x16x32_bf16 v[126:129], v[134:137], v[192:195], v[126:129]
	v_mfma_f32_16x16x32_bf16 v[122:125], v[142:145], v[192:195], v[122:125]
	v_mfma_f32_16x16x32_bf16 v[110:113], v[134:137], v[200:203], v[110:113]
	v_mfma_f32_16x16x32_bf16 v[106:109], v[142:145], v[200:203], v[106:109]
	v_mfma_f32_16x16x32_bf16 v[94:97], v[134:137], v[208:211], v[94:97]
	v_mfma_f32_16x16x32_bf16 v[90:93], v[142:145], v[208:211], v[90:93]
	v_mfma_f32_16x16x32_bf16 v[78:81], v[134:137], v[216:219], v[78:81]
	v_mfma_f32_16x16x32_bf16 v[74:77], v[142:145], v[216:219], v[74:77]
	v_mfma_f32_16x16x32_bf16 v[118:121], v[166:169], v[188:191], v[118:121]
	v_mfma_f32_16x16x32_bf16 v[114:117], v[180:183], v[188:191], v[114:117]
	v_mfma_f32_16x16x32_bf16 v[102:105], v[166:169], v[196:199], v[102:105]
	v_mfma_f32_16x16x32_bf16 v[98:101], v[180:183], v[196:199], v[98:101]
	v_mfma_f32_16x16x32_bf16 v[86:89], v[166:169], v[204:207], v[86:89]
	v_mfma_f32_16x16x32_bf16 v[82:85], v[180:183], v[204:207], v[82:85]
	v_mfma_f32_16x16x32_bf16 v[70:73], v[166:169], v[212:215], v[70:73]
	v_mfma_f32_16x16x32_bf16 v[66:69], v[180:183], v[212:215], v[66:69]
	v_mfma_f32_16x16x32_bf16 v[118:121], v[176:179], v[192:195], v[118:121]
	v_mfma_f32_16x16x32_bf16 v[114:117], v[184:187], v[192:195], v[114:117]
	v_mfma_f32_16x16x32_bf16 v[102:105], v[176:179], v[200:203], v[102:105]
	v_mfma_f32_16x16x32_bf16 v[98:101], v[184:187], v[200:203], v[98:101]
	v_mfma_f32_16x16x32_bf16 v[86:89], v[176:179], v[208:211], v[86:89]
	v_mfma_f32_16x16x32_bf16 v[82:85], v[184:187], v[208:211], v[82:85]
	v_mfma_f32_16x16x32_bf16 v[70:73], v[176:179], v[216:219], v[70:73]
	v_mfma_f32_16x16x32_bf16 v[66:69], v[184:187], v[216:219], v[66:69]
	s_setprio 0
	s_barrier
	s_add_i32 s61, s52, s36
	v_lshl_add_u64 v[170:171], s[26:27], 0, v[150:151]
	s_mov_b32 m0, s61
	ds_read_b128 v[188:191], v174 offset:16384
	ds_read_b128 v[192:195], v174 offset:17408
	ds_read_b128 v[196:199], v174 offset:18432
	ds_read_b128 v[200:203], v174 offset:19456
	ds_read_b128 v[204:207], v174 offset:20480
	ds_read_b128 v[208:211], v174 offset:21504
	ds_read_b128 v[212:215], v174 offset:22528
	ds_read_b128 v[216:219], v174 offset:23552
	global_load_lds_dwordx4 v[170:171], off
	s_add_i32 m0, s61, 0x2000
	s_add_u32 s62, s26, 0x80000
	v_lshl_add_u64 v[220:221], s[26:27], 0, v[146:147]
	s_addc_u32 s63, s27, 0
	s_add_i32 s61, s53, s36
	global_load_lds_dwordx4 v[220:221], off
	v_lshl_add_u64 v[222:223], s[62:63], 0, v[150:151]
	s_mov_b32 m0, s61
	v_lshl_add_u64 v[224:225], s[28:29], 0, v[148:149]
	global_load_lds_dwordx4 v[222:223], off
	v_lshl_add_u64 v[222:223], s[62:63], 0, v[146:147]
	s_add_i32 m0, s61, 0x2000
	s_nop 0
	global_load_lds_dwordx4 v[222:223], off
	v_lshl_add_u64 v[222:223], s[28:29], 0, v[152:153]
	s_mov_b32 m0, s39
	s_nop 0
	global_load_lds_dwordx4 v[222:223], off
	s_mov_b32 m0, s33
	s_nop 0
	global_load_lds_dwordx4 v[224:225], off
	s_waitcnt vmcnt(8)
	s_waitcnt lgkmcnt(0)
	s_barrier
; #define PG8_STAGE(bufoff, gbase, voff) do { _Pragma("unroll") for (int _i = 0; _i < 2; ++_i) \
;         __builtin_amdgcn_global_load_lds((const unsigned*)((const char*)(gbase) + (voff)[_i]), (PG8_LAS unsigned*)(lds + (bufoff) + ldsw + _i * 8192), 16, 0, 0); } while (0)
; #define PG8_LDA(dst, b, h) do { _Pragma("unroll") for (int m = 0; m < 4; ++m) _Pragma("unroll") for (int k = 0; k < 2; ++k) dst[m][k] = *(const PG8_LAS bf16x8*)(lds + PG8_SA(b, h) + aoff + m * 2048 + k * 1024); } while (0)
; #define PG8_LDB(dst, b, h) do { _Pragma("unroll") for (int n = 0; n < 2; ++n) _Pragma("unroll") for (int k = 0; k < 2; ++k) dst[n][k] = *(const PG8_LAS bf16x8*)(lds + PG8_SB(b, h) + boff + n * 2048 + k * 1024); } while (0)
; #define PG8_MMA(ai, bj, At, Bt) do { __builtin_amdgcn_s_setprio(1); _Pragma("unroll") for (int m = 0; m < 4; ++m) _Pragma("unroll") for (int n = 0; n < 2; ++n) _Pragma("unroll") for (int k = 0; k < 2; ++k) \
;         acc[ai][bj][m][n] = __builtin_amdgcn_mfma_f32_16x16x32_bf16(Bt[n][k], At[m][k], acc[ai][bj][m][n], 0, 0, 0); __builtin_amdgcn_s_setprio(0); } while (0)
; #define PG8_WAIT_V(n) asm volatile("s_waitcnt vmcnt(" #n ")" ::: "memory")
; #define PG8_WAIT_L(n) asm volatile("s_waitcnt lgkmcnt(" #n ")" ::: "memory")
; #define PG8_BAR __builtin_amdgcn_s_barrier()
; #define PG8_SCHED __builtin_amdgcn_sched_barrier(0)
; template <class Epi, class Sched>
; __device__ __forceinline__ void gemm_phase(PG8_LAS unsigned char* lds, const Gemm g, const Sched& S, const Epi& E) {
;     ...
;             PG8_WAIT_V(8); PG8_WAIT_L(0); PG8_BAR; PG8_MMA(1, 0, At, B0); PG8_MMA(1, 1, At, B1); PG8_BAR; PG8_SCHED;
;             PG8_LDB(B0, 1, 0); PG8_LDB(B1, 1, 1); PG8_SCHED; PG8_LDA(At, 1, 0); PG8_STAGE(PG8_SA(0, 1), a2 + hstepA, voffA);
;             PG8_WAIT_V(8); PG8_WAIT_L(0); PG8_BAR; PG8_MMA(0, 0, At, B0); PG8_MMA(0, 1, At, B1); PG8_BAR; PG8_SCHED;
;             PG8_LDA(At, 1, 1); PG8_STAGE(PG8_SB(1, 0), b3, voffB); PG8_STAGE(PG8_SB(1, 1), b3 + hstepB, voffB); PG8_STAGE(PG8_SA(1, 0), a3, voffA);
	s_setprio 1
	s_waitcnt lgkmcnt(0)
	v_mfma_f32_16x16x32_bf16 v[62:65], v[130:133], v[188:191], v[62:65]
	v_mfma_f32_16x16x32_bf16 v[58:61], v[138:141], v[188:191], v[58:61]
	v_mfma_f32_16x16x32_bf16 v[46:49], v[130:133], v[196:199], v[46:49]
	v_mfma_f32_16x16x32_bf16 v[42:45], v[138:141], v[196:199], v[42:45]
	v_mfma_f32_16x16x32_bf16 v[30:33], v[130:133], v[204:207], v[30:33]
	v_mfma_f32_16x16x32_bf16 v[26:29], v[138:141], v[204:207], v[26:29]
	v_mfma_f32_16x16x32_bf16 v[14:17], v[130:133], v[212:215], v[14:17]
	v_mfma_f32_16x16x32_bf16 v[10:13], v[138:141], v[212:215], v[10:13]
	v_mfma_f32_16x16x32_bf16 v[62:65], v[134:137], v[192:195], v[62:65]
	v_mfma_f32_16x16x32_bf16 v[58:61], v[142:145], v[192:195], v[58:61]
	v_mfma_f32_16x16x32_bf16 v[46:49], v[134:137], v[200:203], v[46:49]
	v_mfma_f32_16x16x32_bf16 v[42:45], v[142:145], v[200:203], v[42:45]
	v_mfma_f32_16x16x32_bf16 v[30:33], v[134:137], v[208:211], v[30:33]
	v_mfma_f32_16x16x32_bf16 v[26:29], v[142:145], v[208:211], v[26:29]
	v_mfma_f32_16x16x32_bf16 v[14:17], v[134:137], v[216:219], v[14:17]
	v_mfma_f32_16x16x32_bf16 v[10:13], v[142:145], v[216:219], v[10:13]
	v_mfma_f32_16x16x32_bf16 v[54:57], v[166:169], v[188:191], v[54:57]
	v_mfma_f32_16x16x32_bf16 v[50:53], v[180:183], v[188:191], v[50:53]
	v_mfma_f32_16x16x32_bf16 v[38:41], v[166:169], v[196:199], v[38:41]
	v_mfma_f32_16x16x32_bf16 v[34:37], v[180:183], v[196:199], v[34:37]
	v_mfma_f32_16x16x32_bf16 v[22:25], v[166:169], v[204:207], v[22:25]
	v_mfma_f32_16x16x32_bf16 v[18:21], v[180:183], v[204:207], v[18:21]
	v_mfma_f32_16x16x32_bf16 v[6:9], v[166:169], v[212:215], v[6:9]
	v_mfma_f32_16x16x32_bf16 v[2:5], v[180:183], v[212:215], v[2:5]
	v_mfma_f32_16x16x32_bf16 v[54:57], v[176:179], v[192:195], v[54:57]
	v_mfma_f32_16x16x32_bf16 v[50:53], v[184:187], v[192:195], v[50:53]
	v_mfma_f32_16x16x32_bf16 v[38:41], v[176:179], v[200:203], v[38:41]
	v_mfma_f32_16x16x32_bf16 v[34:37], v[184:187], v[200:203], v[34:37]
	v_mfma_f32_16x16x32_bf16 v[22:25], v[176:179], v[208:211], v[22:25]
	v_mfma_f32_16x16x32_bf16 v[18:21], v[184:187], v[208:211], v[18:21]
	v_mfma_f32_16x16x32_bf16 v[6:9], v[176:179], v[216:219], v[6:9]
	v_mfma_f32_16x16x32_bf16 v[2:5], v[184:187], v[216:219], v[2:5]
	s_setprio 0
	s_barrier
	s_add_i32 s61, 0, 0x18000
	s_add_i32 s62, 0, 0x1c000
	v_add_u32_e32 v142, s61, v159
	v_add_u32_e32 v156, s62, v159
	ds_read_b128 v[130:133], v142
	ds_read_b128 v[134:137], v142 offset:1024
	ds_read_b128 v[138:141], v142 offset:2048
	ds_read_b128 v[142:145], v142 offset:3072
	ds_read_b128 v[166:169], v156
	ds_read_b128 v[176:179], v156 offset:1024
	ds_read_b128 v[180:183], v156 offset:2048
	ds_read_b128 v[184:187], v156 offset:3072
	s_add_u32 s28, s28, 0x80000
	s_addc_u32 s29, s29, 0
	s_mov_b32 m0, s40
	v_lshl_add_u64 v[226:227], s[28:29], 0, v[152:153]
	ds_read_b128 v[188:191], v174 offset:32768
	ds_read_b128 v[192:195], v174 offset:33792
	ds_read_b128 v[196:199], v174 offset:34816
	ds_read_b128 v[200:203], v174 offset:35840
	ds_read_b128 v[204:207], v174 offset:36864
	ds_read_b128 v[208:211], v174 offset:37888
	ds_read_b128 v[212:215], v174 offset:38912
	ds_read_b128 v[216:219], v174 offset:39936
	global_load_lds_dwordx4 v[226:227], off
	v_lshl_add_u64 v[226:227], s[28:29], 0, v[148:149]
	s_mov_b32 m0, s41
	s_nop 0
	global_load_lds_dwordx4 v[226:227], off
	s_waitcnt vmcnt(8)
	s_waitcnt lgkmcnt(0)
	s_barrier
	s_setprio 1
	s_waitcnt lgkmcnt(0)
	v_mfma_f32_16x16x32_bf16 v[126:129], v[130:133], v[188:191], v[126:129]
	v_mfma_f32_16x16x32_bf16 v[122:125], v[138:141], v[188:191], v[122:125]
	v_mfma_f32_16x16x32_bf16 v[110:113], v[130:133], v[196:199], v[110:113]
	v_mfma_f32_16x16x32_bf16 v[106:109], v[138:141], v[196:199], v[106:109]
	v_mfma_f32_16x16x32_bf16 v[94:97], v[130:133], v[204:207], v[94:97]
	v_mfma_f32_16x16x32_bf16 v[90:93], v[138:141], v[204:207], v[90:93]
	v_mfma_f32_16x16x32_bf16 v[78:81], v[130:133], v[212:215], v[78:81]
	v_mfma_f32_16x16x32_bf16 v[74:77], v[138:141], v[212:215], v[74:77]
	v_mfma_f32_16x16x32_bf16 v[126:129], v[134:137], v[192:195], v[126:129]
	v_mfma_f32_16x16x32_bf16 v[122:125], v[142:145], v[192:195], v[122:125]
	v_mfma_f32_16x16x32_bf16 v[110:113], v[134:137], v[200:203], v[110:113]
	v_mfma_f32_16x16x32_bf16 v[106:109], v[142:145], v[200:203], v[106:109]
	v_mfma_f32_16x16x32_bf16 v[94:97], v[134:137], v[208:211], v[94:97]
	v_mfma_f32_16x16x32_bf16 v[90:93], v[142:145], v[208:211], v[90:93]
	v_mfma_f32_16x16x32_bf16 v[78:81], v[134:137], v[216:219], v[78:81]
	v_mfma_f32_16x16x32_bf16 v[74:77], v[142:145], v[216:219], v[74:77]
	v_mfma_f32_16x16x32_bf16 v[118:121], v[166:169], v[188:191], v[118:121]
	v_mfma_f32_16x16x32_bf16 v[114:117], v[180:183], v[188:191], v[114:117]
	v_mfma_f32_16x16x32_bf16 v[102:105], v[166:169], v[196:199], v[102:105]
	v_mfma_f32_16x16x32_bf16 v[98:101], v[180:183], v[196:199], v[98:101]
	v_mfma_f32_16x16x32_bf16 v[86:89], v[166:169], v[204:207], v[86:89]
	v_mfma_f32_16x16x32_bf16 v[82:85], v[180:183], v[204:207], v[82:85]
	v_mfma_f32_16x16x32_bf16 v[70:73], v[166:169], v[212:215], v[70:73]
	v_mfma_f32_16x16x32_bf16 v[66:69], v[180:183], v[212:215], v[66:69]
	v_mfma_f32_16x16x32_bf16 v[118:121], v[176:179], v[192:195], v[118:121]
	v_mfma_f32_16x16x32_bf16 v[114:117], v[184:187], v[192:195], v[114:117]
	v_mfma_f32_16x16x32_bf16 v[102:105], v[176:179], v[200:203], v[102:105]
	v_mfma_f32_16x16x32_bf16 v[98:101], v[184:187], v[200:203], v[98:101]
	v_mfma_f32_16x16x32_bf16 v[86:89], v[176:179], v[208:211], v[86:89]
	v_mfma_f32_16x16x32_bf16 v[82:85], v[184:187], v[208:211], v[82:85]
	v_mfma_f32_16x16x32_bf16 v[70:73], v[176:179], v[216:219], v[70:73]
	v_mfma_f32_16x16x32_bf16 v[66:69], v[184:187], v[216:219], v[66:69]
	s_setprio 0
	s_barrier
; #define PG8_STAGE(bufoff, gbase, voff) do { _Pragma("unroll") for (int _i = 0; _i < 2; ++_i) \
;         __builtin_amdgcn_global_load_lds((const unsigned*)((const char*)(gbase) + (voff)[_i]), (PG8_LAS unsigned*)(lds + (bufoff) + ldsw + _i * 8192), 16, 0, 0); } while (0)
; #define PG8_LDA(dst, b, h) do { _Pragma("unroll") for (int m = 0; m < 4; ++m) _Pragma("unroll") for (int k = 0; k < 2; ++k) dst[m][k] = *(const PG8_LAS bf16x8*)(lds + PG8_SA(b, h) + aoff + m * 2048 + k * 1024); } while (0)
; #define PG8_MMA(ai, bj, At, Bt) do { __builtin_amdgcn_s_setprio(1); _Pragma("unroll") for (int m = 0; m < 4; ++m) _Pragma("unroll") for (int n = 0; n < 2; ++n) _Pragma("unroll") for (int k = 0; k < 2; ++k) \
;         acc[ai][bj][m][n] = __builtin_amdgcn_mfma_f32_16x16x32_bf16(Bt[n][k], At[m][k], acc[ai][bj][m][n], 0, 0, 0); __builtin_amdgcn_s_setprio(0); } while (0)
; #define PG8_WAIT_V(n) asm volatile("s_waitcnt vmcnt(" #n ")" ::: "memory")
; #define PG8_WAIT_L(n) asm volatile("s_waitcnt lgkmcnt(" #n ")" ::: "memory")
; #define PG8_BAR __builtin_amdgcn_s_barrier()
; #define PG8_SCHED __builtin_amdgcn_sched_barrier(0)
; template <class Epi, class Sched>
; __device__ __forceinline__ void gemm_phase(PG8_LAS unsigned char* lds, const Gemm g, const Sched& S, const Epi& E) {
;     ...
;             PG8_LDA(At, 1, 1); PG8_STAGE(PG8_SB(1, 0), b3, voffB); PG8_STAGE(PG8_SB(1, 1), b3 + hstepB, voffB); PG8_STAGE(PG8_SA(1, 0), a3, voffA);
;             PG8_WAIT_V(8); PG8_WAIT_L(0); PG8_BAR; PG8_MMA(1, 0, At, B0); PG8_MMA(1, 1, At, B1); PG8_BAR; PG8_SCHED;
;         }
	s_add_i32 s28, s61, s36
	v_lshl_add_u64 v[170:171], v[170:171], 0, s[10:11]
	s_mov_b32 m0, s28
	ds_read_b128 v[188:191], v174 offset:49152
	ds_read_b128 v[192:195], v174 offset:50176
	ds_read_b128 v[196:199], v174 offset:51200
	ds_read_b128 v[200:203], v174 offset:52224
	ds_read_b128 v[204:207], v174 offset:53248
	ds_read_b128 v[208:211], v174 offset:54272
	ds_read_b128 v[212:215], v174 offset:55296
	ds_read_b128 v[216:219], v174 offset:56320
	global_load_lds_dwordx4 v[170:171], off
	s_add_i32 m0, s28, 0x2000
	s_add_u32 s26, s26, 0x80080
	v_lshl_add_u64 v[170:171], v[220:221], 0, s[10:11]
	s_addc_u32 s27, s27, 0
	s_add_i32 s28, s62, s36
	global_load_lds_dwordx4 v[170:171], off
	v_lshl_add_u64 v[170:171], s[26:27], 0, v[150:151]
	s_mov_b32 m0, s28
	s_nop 0
	global_load_lds_dwordx4 v[170:171], off
	v_lshl_add_u64 v[170:171], s[26:27], 0, v[146:147]
	s_add_i32 m0, s28, 0x2000
	s_nop 0
	global_load_lds_dwordx4 v[170:171], off
	v_lshl_add_u64 v[170:171], v[222:223], 0, s[10:11]
	s_mov_b32 m0, s49
	s_nop 0
	global_load_lds_dwordx4 v[170:171], off
	v_lshl_add_u64 v[170:171], v[224:225], 0, s[10:11]
	s_mov_b32 m0, s50
	s_nop 0
	global_load_lds_dwordx4 v[170:171], off
	s_waitcnt vmcnt(8)
	s_waitcnt lgkmcnt(0)
	s_barrier
	s_setprio 1
	s_waitcnt lgkmcnt(0)
	v_mfma_f32_16x16x32_bf16 v[62:65], v[130:133], v[188:191], v[62:65]
	v_mfma_f32_16x16x32_bf16 v[58:61], v[138:141], v[188:191], v[58:61]
	v_mfma_f32_16x16x32_bf16 v[46:49], v[130:133], v[196:199], v[46:49]
	v_mfma_f32_16x16x32_bf16 v[42:45], v[138:141], v[196:199], v[42:45]
	v_mfma_f32_16x16x32_bf16 v[30:33], v[130:133], v[204:207], v[30:33]
	v_mfma_f32_16x16x32_bf16 v[26:29], v[138:141], v[204:207], v[26:29]
	v_mfma_f32_16x16x32_bf16 v[14:17], v[130:133], v[212:215], v[14:17]
	v_mfma_f32_16x16x32_bf16 v[10:13], v[138:141], v[212:215], v[10:13]
	v_mfma_f32_16x16x32_bf16 v[62:65], v[134:137], v[192:195], v[62:65]
	v_mfma_f32_16x16x32_bf16 v[58:61], v[142:145], v[192:195], v[58:61]
	v_mfma_f32_16x16x32_bf16 v[46:49], v[134:137], v[200:203], v[46:49]
	v_mfma_f32_16x16x32_bf16 v[42:45], v[142:145], v[200:203], v[42:45]
	v_mfma_f32_16x16x32_bf16 v[30:33], v[134:137], v[208:211], v[30:33]
	v_mfma_f32_16x16x32_bf16 v[26:29], v[142:145], v[208:211], v[26:29]
	v_mfma_f32_16x16x32_bf16 v[14:17], v[134:137], v[216:219], v[14:17]
	v_mfma_f32_16x16x32_bf16 v[10:13], v[142:145], v[216:219], v[10:13]
	v_mfma_f32_16x16x32_bf16 v[54:57], v[166:169], v[188:191], v[54:57]
	v_mfma_f32_16x16x32_bf16 v[50:53], v[180:183], v[188:191], v[50:53]
	v_mfma_f32_16x16x32_bf16 v[38:41], v[166:169], v[196:199], v[38:41]
	v_mfma_f32_16x16x32_bf16 v[34:37], v[180:183], v[196:199], v[34:37]
	v_mfma_f32_16x16x32_bf16 v[22:25], v[166:169], v[204:207], v[22:25]
	v_mfma_f32_16x16x32_bf16 v[18:21], v[180:183], v[204:207], v[18:21]
	v_mfma_f32_16x16x32_bf16 v[6:9], v[166:169], v[212:215], v[6:9]
	v_mfma_f32_16x16x32_bf16 v[2:5], v[180:183], v[212:215], v[2:5]
	v_mfma_f32_16x16x32_bf16 v[54:57], v[176:179], v[192:195], v[54:57]
	v_mfma_f32_16x16x32_bf16 v[50:53], v[184:187], v[192:195], v[50:53]
	v_mfma_f32_16x16x32_bf16 v[38:41], v[176:179], v[200:203], v[38:41]
	v_mfma_f32_16x16x32_bf16 v[34:37], v[184:187], v[200:203], v[34:37]
	v_mfma_f32_16x16x32_bf16 v[22:25], v[176:179], v[208:211], v[22:25]
	v_mfma_f32_16x16x32_bf16 v[18:21], v[184:187], v[208:211], v[18:21]
	v_mfma_f32_16x16x32_bf16 v[6:9], v[176:179], v[216:219], v[6:9]
	v_mfma_f32_16x16x32_bf16 v[2:5], v[184:187], v[216:219], v[2:5]
	s_setprio 0
	s_barrier
	s_add_i32 s60, s60, 2
	s_add_u32 s24, s24, 0x100
	s_addc_u32 s25, s25, 0
	s_add_u32 s58, s58, 0x100
	s_addc_u32 s59, s59, 0
	s_cmp_gt_u32 s60, 29
	s_cbranch_scc0 .LBB0_791
	s_and_b64 vcc, exec, s[12:13]
	s_cbranch_vccz .LBB0_794
	s_barrier

; #define PG8_STAGE(bufoff, gbase, voff) do { _Pragma("unroll") for (int _i = 0; _i < 2; ++_i) \
;         __builtin_amdgcn_global_load_lds((const unsigned*)((const char*)(gbase) + (voff)[_i]), (PG8_LAS unsigned*)(lds + (bufoff) + ldsw + _i * 8192), 16, 0, 0); } while (0)
; #define PG8_LDA(dst, b, h) do { _Pragma("unroll") for (int m = 0; m < 4; ++m) _Pragma("unroll") for (int k = 0; k < 2; ++k) dst[m][k] = *(const PG8_LAS bf16x8*)(lds + PG8_SA(b, h) + aoff + m * 2048 + k * 1024); } while (0)
; #define PG8_LDB(dst, b, h) do { _Pragma("unroll") for (int n = 0; n < 2; ++n) _Pragma("unroll") for (int k = 0; k < 2; ++k) dst[n][k] = *(const PG8_LAS bf16x8*)(lds + PG8_SB(b, h) + boff + n * 2048 + k * 1024); } while (0)
; #define PG8_MMA(ai, bj, At, Bt) do { __builtin_amdgcn_s_setprio(1); _Pragma("unroll") for (int m = 0; m < 4; ++m) _Pragma("unroll") for (int n = 0; n < 2; ++n) _Pragma("unroll") for (int k = 0; k < 2; ++k) \
;         acc[ai][bj][m][n] = __builtin_amdgcn_mfma_f32_16x16x32_bf16(Bt[n][k], At[m][k], acc[ai][bj][m][n], 0, 0, 0); __builtin_amdgcn_s_setprio(0); } while (0)
; #define PG8_WAIT_V(n) asm volatile("s_waitcnt vmcnt(" #n ")" ::: "memory")
; #define PG8_WAIT_L(n) asm volatile("s_waitcnt lgkmcnt(" #n ")" ::: "memory")
; #define PG8_BAR __builtin_amdgcn_s_barrier()
; #define PG8_SCHED __builtin_amdgcn_sched_barrier(0)
; template <class Epi, class Sched>
; __device__ __forceinline__ void gemm_phase(PG8_LAS unsigned char* lds, const Gemm g, const Sched& S, const Epi& E) {
;     ...
;             PG8_LDB(B0, 0, 0); PG8_LDB(B1, 0, 1); PG8_SCHED; PG8_LDA(At, 0, 0); PG8_STAGE(PG8_SA(1, 1), a1 + hstepA, voffA);
;             PG8_WAIT_V(8); PG8_WAIT_L(0); PG8_BAR; PG8_MMA(0, 0, At, B0); PG8_MMA(0, 1, At, B1); PG8_BAR; PG8_SCHED;
;             PG8_LDA(At, 0, 1); PG8_STAGE(PG8_SB(0, 0), b2, voffB); PG8_STAGE(PG8_SB(0, 1), b2 + hstepB, voffB); PG8_STAGE(PG8_SA(0, 0), a2, voffA);
;             PG8_WAIT_V(8); PG8_WAIT_L(0); PG8_BAR; PG8_MMA(1, 0, At, B0); PG8_MMA(1, 1, At, B1); PG8_BAR; PG8_SCHED;
.LBB0_946:
	ds_read_b128 v[122:125], v170
	ds_read_b128 v[126:129], v170 offset:1024
	ds_read_b128 v[130:133], v170 offset:2048
	ds_read_b128 v[134:137], v170 offset:3072
	ds_read_b128 v[162:165], v171
	ds_read_b128 v[174:177], v171 offset:1024
	ds_read_b128 v[178:181], v171 offset:2048
	ds_read_b128 v[182:185], v171 offset:3072
	s_add_u32 s26, s24, 0xffea0080
	s_addc_u32 s27, s25, -1
	s_cmpk_eq_i32 s56, 0x54
	s_cselect_b32 s29, s3, s27
	s_cselect_b32 s28, s2, s26
	s_cselect_b32 s27, s23, s55
	s_cselect_b32 s26, s22, s54
	v_lshl_add_u64 v[166:167], s[24:25], 0, v[156:157]
	s_add_i32 m0, s38, 0xc000
	ds_read_b128 v[186:189], v172
	ds_read_b128 v[190:193], v172 offset:1024
	ds_read_b128 v[194:197], v172 offset:2048
	ds_read_b128 v[198:201], v172 offset:3072
	ds_read_b128 v[202:205], v172 offset:4096
	ds_read_b128 v[206:209], v172 offset:5120
	ds_read_b128 v[210:213], v172 offset:6144
	ds_read_b128 v[214:217], v172 offset:7168
	global_load_lds_dwordx4 v[166:167], off
	v_lshl_add_u64 v[166:167], s[24:25], 0, v[158:159]
	s_add_i32 m0, s38, 0xe000
	s_nop 0
	global_load_lds_dwordx4 v[166:167], off
	s_waitcnt vmcnt(8)
	s_waitcnt lgkmcnt(0)
	s_barrier
	s_setprio 1
	s_waitcnt lgkmcnt(0)
	v_mfma_f32_16x16x32_bf16 v[142:145], v[122:125], v[186:189], v[142:145]
	v_mfma_f32_16x16x32_bf16 v[138:141], v[130:133], v[186:189], v[138:141]
	v_mfma_f32_16x16x32_bf16 v[110:113], v[122:125], v[194:197], v[110:113]
	v_mfma_f32_16x16x32_bf16 v[106:109], v[130:133], v[194:197], v[106:109]
	v_mfma_f32_16x16x32_bf16 v[94:97], v[122:125], v[202:205], v[94:97]
	v_mfma_f32_16x16x32_bf16 v[90:93], v[130:133], v[202:205], v[90:93]
	v_mfma_f32_16x16x32_bf16 v[78:81], v[122:125], v[210:213], v[78:81]
	v_mfma_f32_16x16x32_bf16 v[74:77], v[130:133], v[210:213], v[74:77]
	v_mfma_f32_16x16x32_bf16 v[142:145], v[126:129], v[190:193], v[142:145]
	v_mfma_f32_16x16x32_bf16 v[138:141], v[134:137], v[190:193], v[138:141]
	v_mfma_f32_16x16x32_bf16 v[110:113], v[126:129], v[198:201], v[110:113]
	v_mfma_f32_16x16x32_bf16 v[106:109], v[134:137], v[198:201], v[106:109]
	v_mfma_f32_16x16x32_bf16 v[94:97], v[126:129], v[206:209], v[94:97]
	v_mfma_f32_16x16x32_bf16 v[90:93], v[134:137], v[206:209], v[90:93]
	v_mfma_f32_16x16x32_bf16 v[78:81], v[126:129], v[214:217], v[78:81]
	v_mfma_f32_16x16x32_bf16 v[74:77], v[134:137], v[214:217], v[74:77]
	v_mfma_f32_16x16x32_bf16 v[118:121], v[162:165], v[186:189], v[118:121]
	v_mfma_f32_16x16x32_bf16 v[114:117], v[178:181], v[186:189], v[114:117]
	v_mfma_f32_16x16x32_bf16 v[102:105], v[162:165], v[194:197], v[102:105]
	v_mfma_f32_16x16x32_bf16 v[98:101], v[178:181], v[194:197], v[98:101]
	v_mfma_f32_16x16x32_bf16 v[86:89], v[162:165], v[202:205], v[86:89]
	v_mfma_f32_16x16x32_bf16 v[82:85], v[178:181], v[202:205], v[82:85]
	v_mfma_f32_16x16x32_bf16 v[70:73], v[162:165], v[210:213], v[70:73]
	v_mfma_f32_16x16x32_bf16 v[66:69], v[178:181], v[210:213], v[66:69]
	v_mfma_f32_16x16x32_bf16 v[118:121], v[174:177], v[190:193], v[118:121]
	v_mfma_f32_16x16x32_bf16 v[114:117], v[182:185], v[190:193], v[114:117]
	v_mfma_f32_16x16x32_bf16 v[102:105], v[174:177], v[198:201], v[102:105]
	v_mfma_f32_16x16x32_bf16 v[98:101], v[182:185], v[198:201], v[98:101]
	v_mfma_f32_16x16x32_bf16 v[86:89], v[174:177], v[206:209], v[86:89]
	v_mfma_f32_16x16x32_bf16 v[82:85], v[182:185], v[206:209], v[82:85]
	v_mfma_f32_16x16x32_bf16 v[70:73], v[174:177], v[214:217], v[70:73]
	v_mfma_f32_16x16x32_bf16 v[66:69], v[182:185], v[214:217], v[66:69]
	s_setprio 0
	s_barrier
	s_add_i32 s57, s48, s37
	v_lshl_add_u64 v[166:167], s[26:27], 0, v[148:149]
	s_mov_b32 m0, s57
	ds_read_b128 v[186:189], v172 offset:16384
	ds_read_b128 v[190:193], v172 offset:17408
	ds_read_b128 v[194:197], v172 offset:18432
	ds_read_b128 v[198:201], v172 offset:19456
	ds_read_b128 v[202:205], v172 offset:20480
	ds_read_b128 v[206:209], v172 offset:21504
	ds_read_b128 v[210:213], v172 offset:22528
	ds_read_b128 v[214:217], v172 offset:23552
	global_load_lds_dwordx4 v[166:167], off
	s_add_i32 m0, s57, 0x2000
	s_add_u32 s58, s26, 0x160000
	v_lshl_add_u64 v[218:219], s[26:27], 0, v[152:153]
	s_addc_u32 s59, s27, 0
	s_add_i32 s57, s49, s37
	global_load_lds_dwordx4 v[218:219], off
	v_lshl_add_u64 v[220:221], s[58:59], 0, v[148:149]
	s_mov_b32 m0, s57
	v_lshl_add_u64 v[222:223], s[28:29], 0, v[150:151]
	global_load_lds_dwordx4 v[220:221], off
	v_lshl_add_u64 v[220:221], s[58:59], 0, v[152:153]
	s_add_i32 m0, s57, 0x2000
	s_nop 0
	global_load_lds_dwordx4 v[220:221], off
	v_lshl_add_u64 v[220:221], s[28:29], 0, v[146:147]
	s_mov_b32 m0, s38
	s_nop 0
	global_load_lds_dwordx4 v[220:221], off
	s_mov_b32 m0, s39
	s_nop 0
	global_load_lds_dwordx4 v[222:223], off
	s_waitcnt vmcnt(8)
	s_waitcnt lgkmcnt(0)
	s_barrier
; #define PG8_STAGE(bufoff, gbase, voff) do { _Pragma("unroll") for (int _i = 0; _i < 2; ++_i) \
;         __builtin_amdgcn_global_load_lds((const unsigned*)((const char*)(gbase) + (voff)[_i]), (PG8_LAS unsigned*)(lds + (bufoff) + ldsw + _i * 8192), 16, 0, 0); } while (0)
; #define PG8_LDA(dst, b, h) do { _Pragma("unroll") for (int m = 0; m < 4; ++m) _Pragma("unroll") for (int k = 0; k < 2; ++k) dst[m][k] = *(const PG8_LAS bf16x8*)(lds + PG8_SA(b, h) + aoff + m * 2048 + k * 1024); } while (0)
; #define PG8_LDB(dst, b, h) do { _Pragma("unroll") for (int n = 0; n < 2; ++n) _Pragma("unroll") for (int k = 0; k < 2; ++k) dst[n][k] = *(const PG8_LAS bf16x8*)(lds + PG8_SB(b, h) + boff + n * 2048 + k * 1024); } while (0)
; #define PG8_MMA(ai, bj, At, Bt) do { __builtin_amdgcn_s_setprio(1); _Pragma("unroll") for (int m = 0; m < 4; ++m) _Pragma("unroll") for (int n = 0; n < 2; ++n) _Pragma("unroll") for (int k = 0; k < 2; ++k) \
;         acc[ai][bj][m][n] = __builtin_amdgcn_mfma_f32_16x16x32_bf16(Bt[n][k], At[m][k], acc[ai][bj][m][n], 0, 0, 0); __builtin_amdgcn_s_setprio(0); } while (0)
; #define PG8_WAIT_V(n) asm volatile("s_waitcnt vmcnt(" #n ")" ::: "memory")
; #define PG8_WAIT_L(n) asm volatile("s_waitcnt lgkmcnt(" #n ")" ::: "memory")
; #define PG8_BAR __builtin_amdgcn_s_barrier()
; #define PG8_SCHED __builtin_amdgcn_sched_barrier(0)
; template <class Epi, class Sched>
; __device__ __forceinline__ void gemm_phase(PG8_LAS unsigned char* lds, const Gemm g, const Sched& S, const Epi& E) {
;     ...
;             PG8_WAIT_V(8); PG8_WAIT_L(0); PG8_BAR; PG8_MMA(1, 0, At, B0); PG8_MMA(1, 1, At, B1); PG8_BAR; PG8_SCHED;
;             PG8_LDB(B0, 1, 0); PG8_LDB(B1, 1, 1); PG8_SCHED; PG8_LDA(At, 1, 0); PG8_STAGE(PG8_SA(0, 1), a2 + hstepA, voffA);
;             PG8_WAIT_V(8); PG8_WAIT_L(0); PG8_BAR; PG8_MMA(0, 0, At, B0); PG8_MMA(0, 1, At, B1); PG8_BAR; PG8_SCHED;
;             PG8_LDA(At, 1, 1); PG8_STAGE(PG8_SB(1, 0), b3, voffB); PG8_STAGE(PG8_SB(1, 1), b3 + hstepB, voffB); PG8_STAGE(PG8_SA(1, 0), a3, voffA);
	s_setprio 1
	s_waitcnt lgkmcnt(0)
	v_mfma_f32_16x16x32_bf16 v[62:65], v[122:125], v[186:189], v[62:65]
	v_mfma_f32_16x16x32_bf16 v[58:61], v[130:133], v[186:189], v[58:61]
	v_mfma_f32_16x16x32_bf16 v[46:49], v[122:125], v[194:197], v[46:49]
	v_mfma_f32_16x16x32_bf16 v[42:45], v[130:133], v[194:197], v[42:45]
	v_mfma_f32_16x16x32_bf16 v[30:33], v[122:125], v[202:205], v[30:33]
	v_mfma_f32_16x16x32_bf16 v[26:29], v[130:133], v[202:205], v[26:29]
	v_mfma_f32_16x16x32_bf16 v[14:17], v[122:125], v[210:213], v[14:17]
	v_mfma_f32_16x16x32_bf16 v[10:13], v[130:133], v[210:213], v[10:13]
	v_mfma_f32_16x16x32_bf16 v[62:65], v[126:129], v[190:193], v[62:65]
	v_mfma_f32_16x16x32_bf16 v[58:61], v[134:137], v[190:193], v[58:61]
	v_mfma_f32_16x16x32_bf16 v[46:49], v[126:129], v[198:201], v[46:49]
	v_mfma_f32_16x16x32_bf16 v[42:45], v[134:137], v[198:201], v[42:45]
	v_mfma_f32_16x16x32_bf16 v[30:33], v[126:129], v[206:209], v[30:33]
	v_mfma_f32_16x16x32_bf16 v[26:29], v[134:137], v[206:209], v[26:29]
	v_mfma_f32_16x16x32_bf16 v[14:17], v[126:129], v[214:217], v[14:17]
	v_mfma_f32_16x16x32_bf16 v[10:13], v[134:137], v[214:217], v[10:13]
	v_mfma_f32_16x16x32_bf16 v[54:57], v[162:165], v[186:189], v[54:57]
	v_mfma_f32_16x16x32_bf16 v[50:53], v[178:181], v[186:189], v[50:53]
	v_mfma_f32_16x16x32_bf16 v[38:41], v[162:165], v[194:197], v[38:41]
	v_mfma_f32_16x16x32_bf16 v[34:37], v[178:181], v[194:197], v[34:37]
	v_mfma_f32_16x16x32_bf16 v[22:25], v[162:165], v[202:205], v[22:25]
	v_mfma_f32_16x16x32_bf16 v[18:21], v[178:181], v[202:205], v[18:21]
	v_mfma_f32_16x16x32_bf16 v[6:9], v[162:165], v[210:213], v[6:9]
	v_mfma_f32_16x16x32_bf16 v[2:5], v[178:181], v[210:213], v[2:5]
	v_mfma_f32_16x16x32_bf16 v[54:57], v[174:177], v[190:193], v[54:57]
	v_mfma_f32_16x16x32_bf16 v[50:53], v[182:185], v[190:193], v[50:53]
	v_mfma_f32_16x16x32_bf16 v[38:41], v[174:177], v[198:201], v[38:41]
	v_mfma_f32_16x16x32_bf16 v[34:37], v[182:185], v[198:201], v[34:37]
	v_mfma_f32_16x16x32_bf16 v[22:25], v[174:177], v[206:209], v[22:25]
	v_mfma_f32_16x16x32_bf16 v[18:21], v[182:185], v[206:209], v[18:21]
	v_mfma_f32_16x16x32_bf16 v[6:9], v[174:177], v[214:217], v[6:9]
	v_mfma_f32_16x16x32_bf16 v[2:5], v[182:185], v[214:217], v[2:5]
	s_setprio 0
	s_barrier
	s_add_i32 s57, 0, 0x18000
	s_add_i32 s58, 0, 0x1c000
	v_add_u32_e32 v134, s57, v168
	v_add_u32_e32 v182, s58, v168
	ds_read_b128 v[122:125], v134
	ds_read_b128 v[126:129], v134 offset:1024
	ds_read_b128 v[130:133], v134 offset:2048
	ds_read_b128 v[134:137], v134 offset:3072
	ds_read_b128 v[162:165], v182
	ds_read_b128 v[174:177], v182 offset:1024
	ds_read_b128 v[178:181], v182 offset:2048
	ds_read_b128 v[182:185], v182 offset:3072
	s_add_u32 s28, s28, 0x160000
	s_addc_u32 s29, s29, 0
	s_mov_b32 m0, s40
	v_lshl_add_u64 v[224:225], s[28:29], 0, v[146:147]
	ds_read_b128 v[186:189], v172 offset:32768
	ds_read_b128 v[190:193], v172 offset:33792
	ds_read_b128 v[194:197], v172 offset:34816
	ds_read_b128 v[198:201], v172 offset:35840
	ds_read_b128 v[202:205], v172 offset:36864
	ds_read_b128 v[206:209], v172 offset:37888
	ds_read_b128 v[210:213], v172 offset:38912
	ds_read_b128 v[214:217], v172 offset:39936
	global_load_lds_dwordx4 v[224:225], off
	v_lshl_add_u64 v[224:225], s[28:29], 0, v[150:151]
	s_mov_b32 m0, s41
	s_nop 0
	global_load_lds_dwordx4 v[224:225], off
	s_waitcnt vmcnt(8)
	s_waitcnt lgkmcnt(0)
	s_barrier
	s_setprio 1
	s_waitcnt lgkmcnt(0)
	v_mfma_f32_16x16x32_bf16 v[142:145], v[122:125], v[186:189], v[142:145]
	v_mfma_f32_16x16x32_bf16 v[138:141], v[130:133], v[186:189], v[138:141]
	v_mfma_f32_16x16x32_bf16 v[110:113], v[122:125], v[194:197], v[110:113]
	v_mfma_f32_16x16x32_bf16 v[106:109], v[130:133], v[194:197], v[106:109]
	v_mfma_f32_16x16x32_bf16 v[94:97], v[122:125], v[202:205], v[94:97]
	v_mfma_f32_16x16x32_bf16 v[90:93], v[130:133], v[202:205], v[90:93]
	v_mfma_f32_16x16x32_bf16 v[78:81], v[122:125], v[210:213], v[78:81]
	v_mfma_f32_16x16x32_bf16 v[74:77], v[130:133], v[210:213], v[74:77]
	v_mfma_f32_16x16x32_bf16 v[142:145], v[126:129], v[190:193], v[142:145]
	v_mfma_f32_16x16x32_bf16 v[138:141], v[134:137], v[190:193], v[138:141]
	v_mfma_f32_16x16x32_bf16 v[110:113], v[126:129], v[198:201], v[110:113]
	v_mfma_f32_16x16x32_bf16 v[106:109], v[134:137], v[198:201], v[106:109]
	v_mfma_f32_16x16x32_bf16 v[94:97], v[126:129], v[206:209], v[94:97]
	v_mfma_f32_16x16x32_bf16 v[90:93], v[134:137], v[206:209], v[90:93]
	v_mfma_f32_16x16x32_bf16 v[78:81], v[126:129], v[214:217], v[78:81]
	v_mfma_f32_16x16x32_bf16 v[74:77], v[134:137], v[214:217], v[74:77]
	v_mfma_f32_16x16x32_bf16 v[118:121], v[162:165], v[186:189], v[118:121]
	v_mfma_f32_16x16x32_bf16 v[114:117], v[178:181], v[186:189], v[114:117]
	v_mfma_f32_16x16x32_bf16 v[102:105], v[162:165], v[194:197], v[102:105]
	v_mfma_f32_16x16x32_bf16 v[98:101], v[178:181], v[194:197], v[98:101]
	v_mfma_f32_16x16x32_bf16 v[86:89], v[162:165], v[202:205], v[86:89]
	v_mfma_f32_16x16x32_bf16 v[82:85], v[178:181], v[202:205], v[82:85]
	v_mfma_f32_16x16x32_bf16 v[70:73], v[162:165], v[210:213], v[70:73]
	v_mfma_f32_16x16x32_bf16 v[66:69], v[178:181], v[210:213], v[66:69]
	v_mfma_f32_16x16x32_bf16 v[118:121], v[174:177], v[190:193], v[118:121]
	v_mfma_f32_16x16x32_bf16 v[114:117], v[182:185], v[190:193], v[114:117]
	v_mfma_f32_16x16x32_bf16 v[102:105], v[174:177], v[198:201], v[102:105]
	v_mfma_f32_16x16x32_bf16 v[98:101], v[182:185], v[198:201], v[98:101]
	v_mfma_f32_16x16x32_bf16 v[86:89], v[174:177], v[206:209], v[86:89]
	v_mfma_f32_16x16x32_bf16 v[82:85], v[182:185], v[206:209], v[82:85]
	v_mfma_f32_16x16x32_bf16 v[70:73], v[174:177], v[214:217], v[70:73]
	v_mfma_f32_16x16x32_bf16 v[66:69], v[182:185], v[214:217], v[66:69]
	s_setprio 0
	s_barrier
; #define PG8_STAGE(bufoff, gbase, voff) do { _Pragma("unroll") for (int _i = 0; _i < 2; ++_i) \
;         __builtin_amdgcn_global_load_lds((const unsigned*)((const char*)(gbase) + (voff)[_i]), (PG8_LAS unsigned*)(lds + (bufoff) + ldsw + _i * 8192), 16, 0, 0); } while (0)
; #define PG8_LDA(dst, b, h) do { _Pragma("unroll") for (int m = 0; m < 4; ++m) _Pragma("unroll") for (int k = 0; k < 2; ++k) dst[m][k] = *(const PG8_LAS bf16x8*)(lds + PG8_SA(b, h) + aoff + m * 2048 + k * 1024); } while (0)
; #define PG8_MMA(ai, bj, At, Bt) do { __builtin_amdgcn_s_setprio(1); _Pragma("unroll") for (int m = 0; m < 4; ++m) _Pragma("unroll") for (int n = 0; n < 2; ++n) _Pragma("unroll") for (int k = 0; k < 2; ++k) \
;         acc[ai][bj][m][n] = __builtin_amdgcn_mfma_f32_16x16x32_bf16(Bt[n][k], At[m][k], acc[ai][bj][m][n], 0, 0, 0); __builtin_amdgcn_s_setprio(0); } while (0)
; #define PG8_WAIT_V(n) asm volatile("s_waitcnt vmcnt(" #n ")" ::: "memory")
; #define PG8_WAIT_L(n) asm volatile("s_waitcnt lgkmcnt(" #n ")" ::: "memory")
; #define PG8_BAR __builtin_amdgcn_s_barrier()
; #define PG8_SCHED __builtin_amdgcn_sched_barrier(0)
; template <class Epi, class Sched>
; __device__ __forceinline__ void gemm_phase(PG8_LAS unsigned char* lds, const Gemm g, const Sched& S, const Epi& E) {
;     ...
;             PG8_LDA(At, 1, 1); PG8_STAGE(PG8_SB(1, 0), b3, voffB); PG8_STAGE(PG8_SB(1, 1), b3 + hstepB, voffB); PG8_STAGE(PG8_SA(1, 0), a3, voffA);
;             PG8_WAIT_V(8); PG8_WAIT_L(0); PG8_BAR; PG8_MMA(1, 0, At, B0); PG8_MMA(1, 1, At, B1); PG8_BAR; PG8_SCHED;
;         }
	s_add_i32 s28, s57, s37
	v_lshl_add_u64 v[166:167], v[166:167], 0, s[10:11]
	s_mov_b32 m0, s28
	ds_read_b128 v[186:189], v172 offset:49152
	ds_read_b128 v[190:193], v172 offset:50176
	ds_read_b128 v[194:197], v172 offset:51200
	ds_read_b128 v[198:201], v172 offset:52224
	ds_read_b128 v[202:205], v172 offset:53248
	ds_read_b128 v[206:209], v172 offset:54272
	ds_read_b128 v[210:213], v172 offset:55296
	ds_read_b128 v[214:217], v172 offset:56320
	global_load_lds_dwordx4 v[166:167], off
	s_add_i32 m0, s28, 0x2000
	s_add_u32 s26, s26, 0x160080
	v_lshl_add_u64 v[166:167], v[218:219], 0, s[10:11]
	s_addc_u32 s27, s27, 0
	s_add_i32 s28, s58, s37
	global_load_lds_dwordx4 v[166:167], off
	v_lshl_add_u64 v[166:167], s[26:27], 0, v[148:149]
	s_mov_b32 m0, s28
	s_nop 0
	global_load_lds_dwordx4 v[166:167], off
	v_lshl_add_u64 v[166:167], s[26:27], 0, v[152:153]
	s_add_i32 m0, s28, 0x2000
	s_nop 0
	global_load_lds_dwordx4 v[166:167], off
	v_lshl_add_u64 v[166:167], v[220:221], 0, s[10:11]
	s_mov_b32 m0, s45
	s_nop 0
	global_load_lds_dwordx4 v[166:167], off
	v_lshl_add_u64 v[166:167], v[222:223], 0, s[10:11]
	s_mov_b32 m0, s46
	s_nop 0
	global_load_lds_dwordx4 v[166:167], off
	s_waitcnt vmcnt(8)
	s_waitcnt lgkmcnt(0)
	s_barrier
	s_setprio 1
	s_waitcnt lgkmcnt(0)
	v_mfma_f32_16x16x32_bf16 v[62:65], v[122:125], v[186:189], v[62:65]
	v_mfma_f32_16x16x32_bf16 v[58:61], v[130:133], v[186:189], v[58:61]
	v_mfma_f32_16x16x32_bf16 v[46:49], v[122:125], v[194:197], v[46:49]
	v_mfma_f32_16x16x32_bf16 v[42:45], v[130:133], v[194:197], v[42:45]
	v_mfma_f32_16x16x32_bf16 v[30:33], v[122:125], v[202:205], v[30:33]
	v_mfma_f32_16x16x32_bf16 v[26:29], v[130:133], v[202:205], v[26:29]
	v_mfma_f32_16x16x32_bf16 v[14:17], v[122:125], v[210:213], v[14:17]
	v_mfma_f32_16x16x32_bf16 v[10:13], v[130:133], v[210:213], v[10:13]
	v_mfma_f32_16x16x32_bf16 v[62:65], v[126:129], v[190:193], v[62:65]
	v_mfma_f32_16x16x32_bf16 v[58:61], v[134:137], v[190:193], v[58:61]
	v_mfma_f32_16x16x32_bf16 v[46:49], v[126:129], v[198:201], v[46:49]
	v_mfma_f32_16x16x32_bf16 v[42:45], v[134:137], v[198:201], v[42:45]
	v_mfma_f32_16x16x32_bf16 v[30:33], v[126:129], v[206:209], v[30:33]
	v_mfma_f32_16x16x32_bf16 v[26:29], v[134:137], v[206:209], v[26:29]
	v_mfma_f32_16x16x32_bf16 v[14:17], v[126:129], v[214:217], v[14:17]
	v_mfma_f32_16x16x32_bf16 v[10:13], v[134:137], v[214:217], v[10:13]
	v_mfma_f32_16x16x32_bf16 v[54:57], v[162:165], v[186:189], v[54:57]
	v_mfma_f32_16x16x32_bf16 v[50:53], v[178:181], v[186:189], v[50:53]
	v_mfma_f32_16x16x32_bf16 v[38:41], v[162:165], v[194:197], v[38:41]
	v_mfma_f32_16x16x32_bf16 v[34:37], v[178:181], v[194:197], v[34:37]
	v_mfma_f32_16x16x32_bf16 v[22:25], v[162:165], v[202:205], v[22:25]
	v_mfma_f32_16x16x32_bf16 v[18:21], v[178:181], v[202:205], v[18:21]
	v_mfma_f32_16x16x32_bf16 v[6:9], v[162:165], v[210:213], v[6:9]
	v_mfma_f32_16x16x32_bf16 v[2:5], v[178:181], v[210:213], v[2:5]
	v_mfma_f32_16x16x32_bf16 v[54:57], v[174:177], v[190:193], v[54:57]
	v_mfma_f32_16x16x32_bf16 v[50:53], v[182:185], v[190:193], v[50:53]
	v_mfma_f32_16x16x32_bf16 v[38:41], v[174:177], v[198:201], v[38:41]
	v_mfma_f32_16x16x32_bf16 v[34:37], v[182:185], v[198:201], v[34:37]
	v_mfma_f32_16x16x32_bf16 v[22:25], v[174:177], v[206:209], v[22:25]
	v_mfma_f32_16x16x32_bf16 v[18:21], v[182:185], v[206:209], v[18:21]
	v_mfma_f32_16x16x32_bf16 v[6:9], v[174:177], v[214:217], v[6:9]
	v_mfma_f32_16x16x32_bf16 v[2:5], v[182:185], v[214:217], v[2:5]
	s_setprio 0
	s_barrier
	s_add_i32 s56, s56, 2
	s_add_u32 s24, s24, 0x100
	s_addc_u32 s25, s25, 0
	s_add_u32 s54, s54, 0x100
	s_addc_u32 s55, s55, 0
	s_cmpk_gt_u32 s56, 0x55
	s_cbranch_scc0 .LBB0_946
	s_and_b64 vcc, exec, s[12:13]
	s_cbranch_vccz .LBB0_949
	s_barrier
